# scan patch + K-loops: per-block setprio flips deleted, static s_setprio 1 for waves 4-7 during each K-loop
# speedup vs baseline: 1.0050x; 1.0050x over previous
.LBB0_131:
	s_ashr_i32 s25, s24, 31
	s_lshl_b64 s[26:27], s[24:25], 21
	s_add_u32 s26, s46, s26
	s_addc_u32 s27, s47, s27
	s_and_b64 s[28:29], s[44:45], exec
	s_cselect_b32 s25, s27, s35
	s_cselect_b32 s61, s26, s34
	s_ashr_i32 s23, s22, 31
	s_lshl_b64 s[28:29], s[22:23], 21
	s_add_u32 s28, s48, s28
	s_addc_u32 s29, s49, s29
	s_and_b64 s[40:41], s[44:45], exec
	s_cselect_b32 s23, s29, s37
	s_cselect_b32 s62, s28, s36
	s_add_u32 s34, s34, 0x100080
	s_addc_u32 s35, s35, 0
	s_add_u32 s63, s36, 0x100
	v_mov_b32_e32 v42, 0
	s_addc_u32 s66, s37, 0
	s_mov_b32 s67, -2
	v_mov_b32_e32 v43, v42
	v_mov_b32_e32 v44, v42
	v_mov_b32_e32 v45, v42
	v_mov_b32_e32 v46, v42
	v_mov_b32_e32 v47, v42
	v_mov_b32_e32 v48, v42
	v_mov_b32_e32 v49, v42
	v_mov_b32_e32 v58, v42
	v_mov_b32_e32 v59, v42
	v_mov_b32_e32 v60, v42
	v_mov_b32_e32 v61, v42
	v_mov_b32_e32 v66, v42
	v_mov_b32_e32 v67, v42
	v_mov_b32_e32 v68, v42
	v_mov_b32_e32 v69, v42
	s_waitcnt vmcnt(0)
	v_mov_b32_e32 v78, v42
	v_mov_b32_e32 v79, v42
	v_mov_b32_e32 v80, v42
	v_mov_b32_e32 v81, v42
	v_mov_b32_e32 v86, v42
	v_mov_b32_e32 v87, v42
	v_mov_b32_e32 v88, v42
	v_mov_b32_e32 v89, v42
	v_mov_b32_e32 v90, v42
	v_mov_b32_e32 v91, v42
	v_mov_b32_e32 v92, v42
	v_mov_b32_e32 v93, v42
	v_mov_b32_e32 v94, v42
	v_mov_b32_e32 v95, v42
	v_mov_b32_e32 v96, v42
	v_mov_b32_e32 v97, v42
	v_mov_b32_e32 v2, v42
	v_mov_b32_e32 v3, v42
	v_mov_b32_e32 v4, v42
	v_mov_b32_e32 v5, v42
	v_mov_b32_e32 v6, v42
	v_mov_b32_e32 v7, v42
	v_mov_b32_e32 v8, v42
	v_mov_b32_e32 v9, v42
	v_mov_b32_e32 v10, v42
	v_mov_b32_e32 v11, v42
	v_mov_b32_e32 v12, v42
	v_mov_b32_e32 v13, v42
	v_mov_b32_e32 v14, v42
	v_mov_b32_e32 v15, v42
	v_mov_b32_e32 v16, v42
	v_mov_b32_e32 v17, v42
	v_mov_b32_e32 v18, v42
	v_mov_b32_e32 v19, v42
	s_waitcnt vmcnt(0)
	v_mov_b32_e32 v20, v42
	v_mov_b32_e32 v21, v42
	v_mov_b32_e32 v22, v42
	v_mov_b32_e32 v23, v42
	v_mov_b32_e32 v24, v42
	v_mov_b32_e32 v25, v42
	v_mov_b32_e32 v26, v42
	v_mov_b32_e32 v27, v42
	v_mov_b32_e32 v28, v42
	v_mov_b32_e32 v29, v42
	v_mov_b32_e32 v30, v42
	v_mov_b32_e32 v31, v42
	v_mov_b32_e32 v32, v42
	v_mov_b32_e32 v33, v42
	v_mov_b32_e32 v98, v42
	v_mov_b32_e32 v99, v42
	v_mov_b32_e32 v100, v42
	v_mov_b32_e32 v101, v42
	v_mov_b32_e32 v102, v42
	v_mov_b32_e32 v103, v42
	v_mov_b32_e32 v104, v42
	v_mov_b32_e32 v105, v42
	v_mov_b32_e32 v106, v42
	v_mov_b32_e32 v107, v42
	v_mov_b32_e32 v108, v42
	v_mov_b32_e32 v109, v42
	v_mov_b32_e32 v110, v42
	v_mov_b32_e32 v111, v42
	v_mov_b32_e32 v112, v42
	v_mov_b32_e32 v113, v42
	v_mov_b32_e32 v114, v42
	v_mov_b32_e32 v115, v42
	v_mov_b32_e32 v116, v42
	v_mov_b32_e32 v117, v42
	v_mov_b32_e32 v118, v42
	v_mov_b32_e32 v119, v42
	v_mov_b32_e32 v120, v42
	v_mov_b32_e32 v121, v42
	v_mov_b32_e32 v122, v42
	v_mov_b32_e32 v123, v42
	v_mov_b32_e32 v124, v42
	v_mov_b32_e32 v125, v42
	v_mov_b32_e32 v126, v42
	v_mov_b32_e32 v127, v42
	v_mov_b32_e32 v128, v42
	v_mov_b32_e32 v129, v42
	v_mov_b32_e32 v34, v42
	v_mov_b32_e32 v35, v42
	v_mov_b32_e32 v36, v42
	v_mov_b32_e32 v37, v42
	v_mov_b32_e32 v38, v42
	v_mov_b32_e32 v39, v42
	v_mov_b32_e32 v40, v42
	v_mov_b32_e32 v41, v42
	v_mov_b32_e32 v50, v42
	v_mov_b32_e32 v51, v42
	v_mov_b32_e32 v52, v42
	v_mov_b32_e32 v53, v42
	v_mov_b32_e32 v54, v42
	v_mov_b32_e32 v55, v42
	v_mov_b32_e32 v56, v42
	v_mov_b32_e32 v57, v42
	v_mov_b32_e32 v62, v42
	v_mov_b32_e32 v63, v42
	v_mov_b32_e32 v64, v42
	v_mov_b32_e32 v65, v42
	v_mov_b32_e32 v70, v42
	v_mov_b32_e32 v71, v42
	v_mov_b32_e32 v72, v42
	v_mov_b32_e32 v73, v42
	v_mov_b32_e32 v74, v42
	v_mov_b32_e32 v75, v42
	v_mov_b32_e32 v76, v42
	v_mov_b32_e32 v77, v42
	v_mov_b32_e32 v82, v42
	v_mov_b32_e32 v83, v42
	v_mov_b32_e32 v84, v42
	v_mov_b32_e32 v85, v42
	v_readfirstlane_b32 s100, v0
	s_cmp_lt_u32 s100, 0x100
	s_cbranch_scc1 .Lprio_skip_132
	s_setprio 1
.Lprio_skip_132:
.LBB0_132:
	s_add_u32 s36, s34, 0xfff00080
	s_addc_u32 s37, s35, -1
	s_add_i32 s68, 0, 0x10000
	s_cmp_eq_u32 s67, 60
	s_cselect_b32 s41, s25, s37
	s_cselect_b32 s40, s61, s36
	v_add_u32_e32 v144, s68, v147
	s_cselect_b32 s37, s23, s66
	s_cselect_b32 s36, s62, s63
	s_add_i32 s70, 0, 0x14000
	s_waitcnt lgkmcnt(0)
	ds_read_b128 v[152:155], v144
	ds_read_b128 v[156:159], v144 offset:1024
	ds_read_b128 v[160:163], v144 offset:2048
	ds_read_b128 v[164:167], v144 offset:3072
	v_add_u32_e32 v144, s70, v147
	ds_read_b128 v[168:171], v144
	ds_read_b128 v[172:175], v144 offset:1024
	ds_read_b128 v[176:179], v144 offset:2048
	ds_read_b128 v[180:183], v144 offset:3072
	v_lshl_add_u64 v[212:213], s[34:35], 0, v[140:141]
	s_add_i32 m0, s51, 0xc000
	ds_read_b128 v[184:187], v151
	ds_read_b128 v[188:191], v151 offset:1024
	ds_read_b128 v[192:195], v151 offset:2048
	ds_read_b128 v[196:199], v151 offset:3072
	ds_read_b128 v[200:203], v151 offset:4096
	ds_read_b128 v[204:207], v151 offset:5120
	ds_read_b128 v[208:211], v151 offset:6144
	ds_read_b128 v[216:219], v151 offset:7168
	global_load_lds_dwordx4 v[212:213], off
	v_lshl_add_u64 v[212:213], s[34:35], 0, v[142:143]
	s_add_i32 m0, s51, 0xe000
	s_nop 0
	global_load_lds_dwordx4 v[212:213], off
	s_waitcnt vmcnt(8)
	s_waitcnt lgkmcnt(0)
	s_barrier
	s_waitcnt lgkmcnt(0)
	v_mfma_f32_16x16x32_bf16 v[82:85], v[152:155], v[184:187], v[82:85]
	v_mfma_f32_16x16x32_bf16 v[74:77], v[160:163], v[184:187], v[74:77]
	v_mfma_f32_16x16x32_bf16 v[70:73], v[152:155], v[192:195], v[70:73]
	v_mfma_f32_16x16x32_bf16 v[62:65], v[160:163], v[192:195], v[62:65]
	v_mfma_f32_16x16x32_bf16 v[54:57], v[152:155], v[200:203], v[54:57]
	v_mfma_f32_16x16x32_bf16 v[50:53], v[160:163], v[200:203], v[50:53]
	v_mfma_f32_16x16x32_bf16 v[38:41], v[152:155], v[208:211], v[38:41]
	v_mfma_f32_16x16x32_bf16 v[34:37], v[160:163], v[208:211], v[34:37]
	v_mfma_f32_16x16x32_bf16 v[82:85], v[156:159], v[188:191], v[82:85]
	v_mfma_f32_16x16x32_bf16 v[74:77], v[164:167], v[188:191], v[74:77]
	v_mfma_f32_16x16x32_bf16 v[70:73], v[156:159], v[196:199], v[70:73]
	v_mfma_f32_16x16x32_bf16 v[62:65], v[164:167], v[196:199], v[62:65]
	v_mfma_f32_16x16x32_bf16 v[54:57], v[156:159], v[204:207], v[54:57]
	v_mfma_f32_16x16x32_bf16 v[50:53], v[164:167], v[204:207], v[50:53]
	v_mfma_f32_16x16x32_bf16 v[38:41], v[156:159], v[216:219], v[38:41]
	v_mfma_f32_16x16x32_bf16 v[34:37], v[164:167], v[216:219], v[34:37]
	v_mfma_f32_16x16x32_bf16 v[126:129], v[168:171], v[184:187], v[126:129]
	v_mfma_f32_16x16x32_bf16 v[122:125], v[176:179], v[184:187], v[122:125]
	v_mfma_f32_16x16x32_bf16 v[118:121], v[168:171], v[192:195], v[118:121]
	v_mfma_f32_16x16x32_bf16 v[114:117], v[176:179], v[192:195], v[114:117]
	v_mfma_f32_16x16x32_bf16 v[110:113], v[168:171], v[200:203], v[110:113]
	v_mfma_f32_16x16x32_bf16 v[106:109], v[176:179], v[200:203], v[106:109]
	v_mfma_f32_16x16x32_bf16 v[102:105], v[168:171], v[208:211], v[102:105]
	v_mfma_f32_16x16x32_bf16 v[98:101], v[176:179], v[208:211], v[98:101]
	v_mfma_f32_16x16x32_bf16 v[126:129], v[172:175], v[188:191], v[126:129]
	v_mfma_f32_16x16x32_bf16 v[122:125], v[180:183], v[188:191], v[122:125]
	v_mfma_f32_16x16x32_bf16 v[118:121], v[172:175], v[196:199], v[118:121]
	v_mfma_f32_16x16x32_bf16 v[114:117], v[180:183], v[196:199], v[114:117]
	v_mfma_f32_16x16x32_bf16 v[110:113], v[172:175], v[204:207], v[110:113]
	v_mfma_f32_16x16x32_bf16 v[106:109], v[180:183], v[204:207], v[106:109]
	v_mfma_f32_16x16x32_bf16 v[102:105], v[172:175], v[216:219], v[102:105]
	v_mfma_f32_16x16x32_bf16 v[98:101], v[180:183], v[216:219], v[98:101]
	s_barrier
	s_add_i32 s68, s68, s50
	v_lshl_add_u64 v[212:213], s[36:37], 0, v[130:131]
	s_mov_b32 m0, s68
	ds_read_b128 v[184:187], v151 offset:16384
	ds_read_b128 v[188:191], v151 offset:17408
	ds_read_b128 v[192:195], v151 offset:18432
	ds_read_b128 v[196:199], v151 offset:19456
	ds_read_b128 v[200:203], v151 offset:20480
	ds_read_b128 v[204:207], v151 offset:21504
	ds_read_b128 v[208:211], v151 offset:22528
	ds_read_b128 v[216:219], v151 offset:23552
	global_load_lds_dwordx4 v[212:213], off
	s_add_i32 m0, s68, 0x2000
	s_add_u32 s68, s36, 0x100000
	v_lshl_add_u64 v[220:221], s[36:37], 0, v[132:133]
	s_addc_u32 s69, s37, 0
	s_add_i32 s70, s70, s50
	global_load_lds_dwordx4 v[220:221], off
	v_lshl_add_u64 v[222:223], s[68:69], 0, v[130:131]
	s_mov_b32 m0, s70
	v_lshl_add_u64 v[224:225], s[40:41], 0, v[134:135]
	global_load_lds_dwordx4 v[222:223], off
	v_lshl_add_u64 v[222:223], s[68:69], 0, v[132:133]
	s_add_i32 m0, s70, 0x2000
	s_nop 0
	global_load_lds_dwordx4 v[222:223], off
	v_lshl_add_u64 v[222:223], s[40:41], 0, v[136:137]
	s_mov_b32 m0, s51
	s_nop 0
	global_load_lds_dwordx4 v[222:223], off
	s_mov_b32 m0, s52
	s_nop 0
	global_load_lds_dwordx4 v[224:225], off
	s_waitcnt vmcnt(8)
	s_waitcnt lgkmcnt(0)
	s_barrier
	s_waitcnt lgkmcnt(0)
	v_mfma_f32_16x16x32_bf16 v[30:33], v[152:155], v[184:187], v[30:33]
	v_mfma_f32_16x16x32_bf16 v[26:29], v[160:163], v[184:187], v[26:29]
	v_mfma_f32_16x16x32_bf16 v[22:25], v[152:155], v[192:195], v[22:25]
	v_mfma_f32_16x16x32_bf16 v[18:21], v[160:163], v[192:195], v[18:21]
	v_mfma_f32_16x16x32_bf16 v[14:17], v[152:155], v[200:203], v[14:17]
	v_mfma_f32_16x16x32_bf16 v[10:13], v[160:163], v[200:203], v[10:13]
	v_mfma_f32_16x16x32_bf16 v[6:9], v[152:155], v[208:211], v[6:9]
	v_mfma_f32_16x16x32_bf16 v[2:5], v[160:163], v[208:211], v[2:5]
	v_mfma_f32_16x16x32_bf16 v[30:33], v[156:159], v[188:191], v[30:33]
	v_mfma_f32_16x16x32_bf16 v[26:29], v[164:167], v[188:191], v[26:29]
	v_mfma_f32_16x16x32_bf16 v[22:25], v[156:159], v[196:199], v[22:25]
	v_mfma_f32_16x16x32_bf16 v[18:21], v[164:167], v[196:199], v[18:21]
	v_mfma_f32_16x16x32_bf16 v[14:17], v[156:159], v[204:207], v[14:17]
	v_mfma_f32_16x16x32_bf16 v[10:13], v[164:167], v[204:207], v[10:13]
	v_mfma_f32_16x16x32_bf16 v[6:9], v[156:159], v[216:219], v[6:9]
	v_mfma_f32_16x16x32_bf16 v[2:5], v[164:167], v[216:219], v[2:5]
	v_mfma_f32_16x16x32_bf16 v[94:97], v[168:171], v[184:187], v[94:97]
	v_mfma_f32_16x16x32_bf16 v[90:93], v[176:179], v[184:187], v[90:93]
	v_mfma_f32_16x16x32_bf16 v[86:89], v[168:171], v[192:195], v[86:89]
	v_mfma_f32_16x16x32_bf16 v[78:81], v[176:179], v[192:195], v[78:81]
	v_mfma_f32_16x16x32_bf16 v[66:69], v[168:171], v[200:203], v[66:69]
	v_mfma_f32_16x16x32_bf16 v[58:61], v[176:179], v[200:203], v[58:61]
	v_mfma_f32_16x16x32_bf16 v[46:49], v[168:171], v[208:211], v[46:49]
	v_mfma_f32_16x16x32_bf16 v[42:45], v[176:179], v[208:211], v[42:45]
	v_mfma_f32_16x16x32_bf16 v[94:97], v[172:175], v[188:191], v[94:97]
	v_mfma_f32_16x16x32_bf16 v[90:93], v[180:183], v[188:191], v[90:93]
	v_mfma_f32_16x16x32_bf16 v[86:89], v[172:175], v[196:199], v[86:89]
	v_mfma_f32_16x16x32_bf16 v[78:81], v[180:183], v[196:199], v[78:81]
	v_mfma_f32_16x16x32_bf16 v[66:69], v[172:175], v[204:207], v[66:69]
	v_mfma_f32_16x16x32_bf16 v[58:61], v[180:183], v[204:207], v[58:61]
	v_mfma_f32_16x16x32_bf16 v[46:49], v[172:175], v[216:219], v[46:49]
	v_mfma_f32_16x16x32_bf16 v[42:45], v[180:183], v[216:219], v[42:45]
	s_barrier
	s_add_i32 s68, 0, 0x18000
	v_add_u32_e32 v144, s68, v147
	s_add_i32 s69, 0, 0x1c000
	ds_read_b128 v[152:155], v144
	ds_read_b128 v[156:159], v144 offset:1024
	ds_read_b128 v[160:163], v144 offset:2048
	ds_read_b128 v[164:167], v144 offset:3072
	v_add_u32_e32 v144, s69, v147
	ds_read_b128 v[168:171], v144
	ds_read_b128 v[172:175], v144 offset:1024
	ds_read_b128 v[176:179], v144 offset:2048
	ds_read_b128 v[180:183], v144 offset:3072
	s_add_u32 s40, s40, 0x100000
	s_addc_u32 s41, s41, 0
	s_mov_b32 m0, s53
	v_lshl_add_u64 v[226:227], s[40:41], 0, v[136:137]
	ds_read_b128 v[184:187], v151 offset:32768
	ds_read_b128 v[188:191], v151 offset:33792
	ds_read_b128 v[192:195], v151 offset:34816
	ds_read_b128 v[196:199], v151 offset:35840
	ds_read_b128 v[200:203], v151 offset:36864
	ds_read_b128 v[204:207], v151 offset:37888
	ds_read_b128 v[208:211], v151 offset:38912
	ds_read_b128 v[216:219], v151 offset:39936
	global_load_lds_dwordx4 v[226:227], off
	v_lshl_add_u64 v[226:227], s[40:41], 0, v[134:135]
	s_mov_b32 m0, s54
	s_nop 0
	global_load_lds_dwordx4 v[226:227], off
	s_waitcnt vmcnt(8)
	s_waitcnt lgkmcnt(0)
	s_barrier
	s_waitcnt lgkmcnt(0)
	v_mfma_f32_16x16x32_bf16 v[82:85], v[152:155], v[184:187], v[82:85]
	v_mfma_f32_16x16x32_bf16 v[74:77], v[160:163], v[184:187], v[74:77]
	v_mfma_f32_16x16x32_bf16 v[70:73], v[152:155], v[192:195], v[70:73]
	v_mfma_f32_16x16x32_bf16 v[62:65], v[160:163], v[192:195], v[62:65]
	v_mfma_f32_16x16x32_bf16 v[54:57], v[152:155], v[200:203], v[54:57]
	v_mfma_f32_16x16x32_bf16 v[50:53], v[160:163], v[200:203], v[50:53]
	v_mfma_f32_16x16x32_bf16 v[38:41], v[152:155], v[208:211], v[38:41]
	v_mfma_f32_16x16x32_bf16 v[34:37], v[160:163], v[208:211], v[34:37]
	v_mfma_f32_16x16x32_bf16 v[82:85], v[156:159], v[188:191], v[82:85]
	v_mfma_f32_16x16x32_bf16 v[74:77], v[164:167], v[188:191], v[74:77]
	v_mfma_f32_16x16x32_bf16 v[70:73], v[156:159], v[196:199], v[70:73]
	v_mfma_f32_16x16x32_bf16 v[62:65], v[164:167], v[196:199], v[62:65]
	v_mfma_f32_16x16x32_bf16 v[54:57], v[156:159], v[204:207], v[54:57]
	v_mfma_f32_16x16x32_bf16 v[50:53], v[164:167], v[204:207], v[50:53]
	v_mfma_f32_16x16x32_bf16 v[38:41], v[156:159], v[216:219], v[38:41]
	v_mfma_f32_16x16x32_bf16 v[34:37], v[164:167], v[216:219], v[34:37]
	v_mfma_f32_16x16x32_bf16 v[126:129], v[168:171], v[184:187], v[126:129]
	v_mfma_f32_16x16x32_bf16 v[122:125], v[176:179], v[184:187], v[122:125]
	v_mfma_f32_16x16x32_bf16 v[118:121], v[168:171], v[192:195], v[118:121]
	v_mfma_f32_16x16x32_bf16 v[114:117], v[176:179], v[192:195], v[114:117]
	v_mfma_f32_16x16x32_bf16 v[110:113], v[168:171], v[200:203], v[110:113]
	v_mfma_f32_16x16x32_bf16 v[106:109], v[176:179], v[200:203], v[106:109]
	v_mfma_f32_16x16x32_bf16 v[102:105], v[168:171], v[208:211], v[102:105]
	v_mfma_f32_16x16x32_bf16 v[98:101], v[176:179], v[208:211], v[98:101]
	v_mfma_f32_16x16x32_bf16 v[126:129], v[172:175], v[188:191], v[126:129]
	v_mfma_f32_16x16x32_bf16 v[122:125], v[180:183], v[188:191], v[122:125]
	v_mfma_f32_16x16x32_bf16 v[118:121], v[172:175], v[196:199], v[118:121]
	v_mfma_f32_16x16x32_bf16 v[114:117], v[180:183], v[196:199], v[114:117]
	v_mfma_f32_16x16x32_bf16 v[110:113], v[172:175], v[204:207], v[110:113]
	v_mfma_f32_16x16x32_bf16 v[106:109], v[180:183], v[204:207], v[106:109]
	v_mfma_f32_16x16x32_bf16 v[102:105], v[172:175], v[216:219], v[102:105]
	v_mfma_f32_16x16x32_bf16 v[98:101], v[180:183], v[216:219], v[98:101]
	s_barrier
	s_add_i32 s40, s68, s50
	v_lshl_add_u64 v[212:213], v[212:213], 0, s[18:19]
	s_mov_b32 m0, s40
	ds_read_b128 v[184:187], v151 offset:49152
	ds_read_b128 v[188:191], v151 offset:50176
	ds_read_b128 v[192:195], v151 offset:51200
	ds_read_b128 v[196:199], v151 offset:52224
	ds_read_b128 v[200:203], v151 offset:53248
	ds_read_b128 v[204:207], v151 offset:54272
	ds_read_b128 v[208:211], v151 offset:55296
	ds_read_b128 v[216:219], v151 offset:56320
	global_load_lds_dwordx4 v[212:213], off
	s_add_i32 m0, s40, 0x2000
	s_add_u32 s36, s36, 0x100080
	v_lshl_add_u64 v[212:213], v[220:221], 0, s[18:19]
	s_addc_u32 s37, s37, 0
	s_add_i32 s40, s69, s50
	global_load_lds_dwordx4 v[212:213], off
	v_lshl_add_u64 v[212:213], s[36:37], 0, v[130:131]
	s_mov_b32 m0, s40
	s_nop 0
	global_load_lds_dwordx4 v[212:213], off
	v_lshl_add_u64 v[212:213], s[36:37], 0, v[132:133]
	s_add_i32 m0, s40, 0x2000
	s_nop 0
	global_load_lds_dwordx4 v[212:213], off
	v_lshl_add_u64 v[212:213], v[222:223], 0, s[18:19]
	s_mov_b32 m0, s30
	s_nop 0
	global_load_lds_dwordx4 v[212:213], off
	v_lshl_add_u64 v[212:213], v[224:225], 0, s[18:19]
	s_mov_b32 m0, s55
	s_nop 0
	global_load_lds_dwordx4 v[212:213], off
	s_waitcnt vmcnt(8)
	s_waitcnt lgkmcnt(0)
	s_barrier
	s_waitcnt lgkmcnt(0)
	v_mfma_f32_16x16x32_bf16 v[30:33], v[152:155], v[184:187], v[30:33]
	v_mfma_f32_16x16x32_bf16 v[26:29], v[160:163], v[184:187], v[26:29]
	v_mfma_f32_16x16x32_bf16 v[22:25], v[152:155], v[192:195], v[22:25]
	v_mfma_f32_16x16x32_bf16 v[18:21], v[160:163], v[192:195], v[18:21]
	v_mfma_f32_16x16x32_bf16 v[14:17], v[152:155], v[200:203], v[14:17]
	v_mfma_f32_16x16x32_bf16 v[10:13], v[160:163], v[200:203], v[10:13]
	v_mfma_f32_16x16x32_bf16 v[6:9], v[152:155], v[208:211], v[6:9]
	v_mfma_f32_16x16x32_bf16 v[2:5], v[160:163], v[208:211], v[2:5]
	v_mfma_f32_16x16x32_bf16 v[30:33], v[156:159], v[188:191], v[30:33]
	v_mfma_f32_16x16x32_bf16 v[26:29], v[164:167], v[188:191], v[26:29]
	v_mfma_f32_16x16x32_bf16 v[22:25], v[156:159], v[196:199], v[22:25]
	v_mfma_f32_16x16x32_bf16 v[18:21], v[164:167], v[196:199], v[18:21]
	v_mfma_f32_16x16x32_bf16 v[14:17], v[156:159], v[204:207], v[14:17]
	v_mfma_f32_16x16x32_bf16 v[10:13], v[164:167], v[204:207], v[10:13]
	v_mfma_f32_16x16x32_bf16 v[6:9], v[156:159], v[216:219], v[6:9]
	v_mfma_f32_16x16x32_bf16 v[2:5], v[164:167], v[216:219], v[2:5]
	v_mfma_f32_16x16x32_bf16 v[94:97], v[168:171], v[184:187], v[94:97]
	v_mfma_f32_16x16x32_bf16 v[90:93], v[176:179], v[184:187], v[90:93]
	v_mfma_f32_16x16x32_bf16 v[86:89], v[168:171], v[192:195], v[86:89]
	v_mfma_f32_16x16x32_bf16 v[78:81], v[176:179], v[192:195], v[78:81]
	v_mfma_f32_16x16x32_bf16 v[66:69], v[168:171], v[200:203], v[66:69]
	v_mfma_f32_16x16x32_bf16 v[58:61], v[176:179], v[200:203], v[58:61]
	v_mfma_f32_16x16x32_bf16 v[46:49], v[168:171], v[208:211], v[46:49]
	v_mfma_f32_16x16x32_bf16 v[42:45], v[176:179], v[208:211], v[42:45]
	v_mfma_f32_16x16x32_bf16 v[94:97], v[172:175], v[188:191], v[94:97]
	v_mfma_f32_16x16x32_bf16 v[90:93], v[180:183], v[188:191], v[90:93]
	v_mfma_f32_16x16x32_bf16 v[86:89], v[172:175], v[196:199], v[86:89]
	v_mfma_f32_16x16x32_bf16 v[78:81], v[180:183], v[196:199], v[78:81]
	v_mfma_f32_16x16x32_bf16 v[66:69], v[172:175], v[204:207], v[66:69]
	v_mfma_f32_16x16x32_bf16 v[58:61], v[180:183], v[204:207], v[58:61]
	v_mfma_f32_16x16x32_bf16 v[46:49], v[172:175], v[216:219], v[46:49]
	v_mfma_f32_16x16x32_bf16 v[42:45], v[180:183], v[216:219], v[42:45]
	s_barrier
	s_add_i32 s67, s67, 2
	s_add_u32 s34, s34, 0x100
	s_addc_u32 s35, s35, 0
	s_add_u32 s63, s63, 0x100
	s_addc_u32 s66, s66, 0
	s_cmp_gt_u32 s67, 61
	s_cbranch_scc0 .LBB0_132
	s_setprio 0
	s_and_b64 vcc, exec, s[12:13]
	s_cbranch_vccz .LBB0_135
	s_barrier

.LBB0_871:
	s_ashr_i32 s13, s12, 31
	s_lshl_b64 s[16:17], s[12:13], 21
	s_add_u32 s16, s34, s16
	s_addc_u32 s17, s35, s17
	s_and_b64 s[22:23], s[42:43], exec
	s_cselect_b32 s13, s17, s25
	s_cselect_b32 s51, s16, s24
	s_ashr_i32 s9, s8, 31
	s_lshl_b64 s[22:23], s[8:9], 21
	s_add_u32 s22, s36, s22
	s_addc_u32 s23, s37, s23
	s_and_b64 s[28:29], s[42:43], exec
	s_cselect_b32 s9, s23, s27
	s_cselect_b32 s52, s22, s26
	s_add_u32 s24, s24, 0x100080
	s_addc_u32 s25, s25, 0
	s_add_u32 s53, s26, 0x100
	v_mov_b32_e32 v2, 0
	s_addc_u32 s54, s27, 0
	s_mov_b32 s55, -2
	v_mov_b32_e32 v3, v2
	v_mov_b32_e32 v4, v2
	s_waitcnt lgkmcnt(0)
	v_mov_b32_e32 v5, v2
	v_mov_b32_e32 v6, v2
	v_mov_b32_e32 v7, v2
	v_mov_b32_e32 v8, v2
	v_mov_b32_e32 v9, v2
	v_mov_b32_e32 v18, v2
	v_mov_b32_e32 v19, v2
	v_mov_b32_e32 v20, v2
	v_mov_b32_e32 v21, v2
	v_mov_b32_e32 v22, v2
	v_mov_b32_e32 v23, v2
	v_mov_b32_e32 v24, v2
	v_mov_b32_e32 v25, v2
	v_mov_b32_e32 v34, v2
	v_mov_b32_e32 v35, v2
	v_mov_b32_e32 v36, v2
	v_mov_b32_e32 v37, v2
	v_mov_b32_e32 v38, v2
	v_mov_b32_e32 v39, v2
	v_mov_b32_e32 v40, v2
	v_mov_b32_e32 v41, v2
	v_mov_b32_e32 v50, v2
	v_mov_b32_e32 v51, v2
	v_mov_b32_e32 v52, v2
	v_mov_b32_e32 v53, v2
	v_mov_b32_e32 v54, v2
	v_mov_b32_e32 v55, v2
	v_mov_b32_e32 v56, v2
	v_mov_b32_e32 v57, v2
	v_mov_b32_e32 v10, v2
	v_mov_b32_e32 v11, v2
	v_mov_b32_e32 v12, v2
	v_mov_b32_e32 v13, v2
	v_mov_b32_e32 v14, v2
	v_mov_b32_e32 v15, v2
	v_mov_b32_e32 v16, v2
	v_mov_b32_e32 v17, v2
	v_mov_b32_e32 v26, v2
	v_mov_b32_e32 v27, v2
	v_mov_b32_e32 v28, v2
	v_mov_b32_e32 v29, v2
	v_mov_b32_e32 v30, v2
	v_mov_b32_e32 v31, v2
	v_mov_b32_e32 v32, v2
	v_mov_b32_e32 v33, v2
	v_mov_b32_e32 v42, v2
	v_mov_b32_e32 v43, v2
	v_mov_b32_e32 v44, v2
	v_mov_b32_e32 v45, v2
	v_mov_b32_e32 v46, v2
	v_mov_b32_e32 v47, v2
	v_mov_b32_e32 v48, v2
	v_mov_b32_e32 v49, v2
	v_mov_b32_e32 v58, v2
	v_mov_b32_e32 v59, v2
	v_mov_b32_e32 v60, v2
	v_mov_b32_e32 v61, v2
	v_mov_b32_e32 v62, v2
	v_mov_b32_e32 v63, v2
	v_mov_b32_e32 v64, v2
	v_mov_b32_e32 v65, v2
	v_mov_b32_e32 v66, v2
	v_mov_b32_e32 v67, v2
	v_mov_b32_e32 v68, v2
	v_mov_b32_e32 v69, v2
	v_mov_b32_e32 v70, v2
	v_mov_b32_e32 v71, v2
	v_mov_b32_e32 v72, v2
	v_mov_b32_e32 v73, v2
	v_mov_b32_e32 v82, v2
	v_mov_b32_e32 v83, v2
	v_mov_b32_e32 v84, v2
	v_mov_b32_e32 v85, v2
	v_mov_b32_e32 v86, v2
	v_mov_b32_e32 v87, v2
	v_mov_b32_e32 v88, v2
	v_mov_b32_e32 v89, v2
	v_mov_b32_e32 v98, v2
	v_mov_b32_e32 v99, v2
	v_mov_b32_e32 v100, v2
	v_mov_b32_e32 v101, v2
	v_mov_b32_e32 v102, v2
	v_mov_b32_e32 v103, v2
	v_mov_b32_e32 v104, v2
	v_mov_b32_e32 v105, v2
	v_mov_b32_e32 v114, v2
	v_mov_b32_e32 v115, v2
	v_mov_b32_e32 v116, v2
	v_mov_b32_e32 v117, v2
	v_mov_b32_e32 v118, v2
	v_mov_b32_e32 v119, v2
	v_mov_b32_e32 v120, v2
	v_mov_b32_e32 v121, v2
	v_mov_b32_e32 v74, v2
	v_mov_b32_e32 v75, v2
	v_mov_b32_e32 v76, v2
	v_mov_b32_e32 v77, v2
	v_mov_b32_e32 v78, v2
	v_mov_b32_e32 v79, v2
	v_mov_b32_e32 v80, v2
	v_mov_b32_e32 v81, v2
	v_mov_b32_e32 v90, v2
	v_mov_b32_e32 v91, v2
	v_mov_b32_e32 v92, v2
	v_mov_b32_e32 v93, v2
	v_mov_b32_e32 v94, v2
	v_mov_b32_e32 v95, v2
	v_mov_b32_e32 v96, v2
	v_mov_b32_e32 v97, v2
	v_mov_b32_e32 v106, v2
	v_mov_b32_e32 v107, v2
	v_mov_b32_e32 v108, v2
	v_mov_b32_e32 v109, v2
	v_mov_b32_e32 v110, v2
	v_mov_b32_e32 v111, v2
	v_mov_b32_e32 v112, v2
	v_mov_b32_e32 v113, v2
	v_mov_b32_e32 v122, v2
	v_mov_b32_e32 v123, v2
	v_mov_b32_e32 v124, v2
	v_mov_b32_e32 v125, v2
	v_mov_b32_e32 v126, v2
	v_mov_b32_e32 v127, v2
	v_mov_b32_e32 v128, v2
	v_mov_b32_e32 v129, v2
	v_readfirstlane_b32 s100, v0
	s_cmp_lt_u32 s100, 0x100
	s_cbranch_scc1 .Lprio_skip_872
	s_setprio 1
.Lprio_skip_872:
.LBB0_872:
	s_add_u32 s26, s24, 0xfff00080
	s_addc_u32 s27, s25, -1
	s_add_i32 s56, 0, 0x10000
	s_cmp_eq_u32 s55, 60
	s_cselect_b32 s29, s13, s27
	s_cselect_b32 s28, s51, s26
	v_add_u32_e32 v148, s56, v152
	s_cselect_b32 s27, s9, s54
	s_cselect_b32 s26, s52, s53
	s_add_i32 s58, 0, 0x14000
	ds_read_b128 v[144:147], v148
	ds_read_b128 v[156:159], v148 offset:1024
	ds_read_b128 v[160:163], v148 offset:2048
	ds_read_b128 v[164:167], v148 offset:3072
	v_add_u32_e32 v148, s58, v152
	ds_read_b128 v[168:171], v148
	ds_read_b128 v[172:175], v148 offset:1024
	ds_read_b128 v[176:179], v148 offset:2048
	ds_read_b128 v[180:183], v148 offset:3072
	v_lshl_add_u64 v[148:149], s[24:25], 0, v[140:141]
	s_add_i32 m0, s41, 0xc000
	ds_read_b128 v[184:187], v154
	ds_read_b128 v[188:191], v154 offset:1024
	ds_read_b128 v[192:195], v154 offset:2048
	ds_read_b128 v[196:199], v154 offset:3072
	ds_read_b128 v[200:203], v154 offset:4096
	ds_read_b128 v[204:207], v154 offset:5120
	ds_read_b128 v[208:211], v154 offset:6144
	ds_read_b128 v[216:219], v154 offset:7168
	global_load_lds_dwordx4 v[148:149], off
	v_lshl_add_u64 v[148:149], s[24:25], 0, v[142:143]
	s_add_i32 m0, s41, 0xe000
	s_nop 0
	global_load_lds_dwordx4 v[148:149], off
	s_waitcnt vmcnt(8)
	s_waitcnt lgkmcnt(0)
	s_barrier
	s_waitcnt lgkmcnt(0)
	v_mfma_f32_16x16x32_bf16 v[126:129], v[144:147], v[184:187], v[126:129]
	v_mfma_f32_16x16x32_bf16 v[122:125], v[160:163], v[184:187], v[122:125]
	v_mfma_f32_16x16x32_bf16 v[110:113], v[144:147], v[192:195], v[110:113]
	v_mfma_f32_16x16x32_bf16 v[106:109], v[160:163], v[192:195], v[106:109]
	v_mfma_f32_16x16x32_bf16 v[94:97], v[144:147], v[200:203], v[94:97]
	v_mfma_f32_16x16x32_bf16 v[90:93], v[160:163], v[200:203], v[90:93]
	v_mfma_f32_16x16x32_bf16 v[78:81], v[144:147], v[208:211], v[78:81]
	v_mfma_f32_16x16x32_bf16 v[74:77], v[160:163], v[208:211], v[74:77]
	v_mfma_f32_16x16x32_bf16 v[126:129], v[156:159], v[188:191], v[126:129]
	v_mfma_f32_16x16x32_bf16 v[122:125], v[164:167], v[188:191], v[122:125]
	v_mfma_f32_16x16x32_bf16 v[110:113], v[156:159], v[196:199], v[110:113]
	v_mfma_f32_16x16x32_bf16 v[106:109], v[164:167], v[196:199], v[106:109]
	v_mfma_f32_16x16x32_bf16 v[94:97], v[156:159], v[204:207], v[94:97]
	v_mfma_f32_16x16x32_bf16 v[90:93], v[164:167], v[204:207], v[90:93]
	v_mfma_f32_16x16x32_bf16 v[78:81], v[156:159], v[216:219], v[78:81]
	v_mfma_f32_16x16x32_bf16 v[74:77], v[164:167], v[216:219], v[74:77]
	v_mfma_f32_16x16x32_bf16 v[118:121], v[168:171], v[184:187], v[118:121]
	v_mfma_f32_16x16x32_bf16 v[114:117], v[176:179], v[184:187], v[114:117]
	v_mfma_f32_16x16x32_bf16 v[102:105], v[168:171], v[192:195], v[102:105]
	v_mfma_f32_16x16x32_bf16 v[98:101], v[176:179], v[192:195], v[98:101]
	v_mfma_f32_16x16x32_bf16 v[86:89], v[168:171], v[200:203], v[86:89]
	v_mfma_f32_16x16x32_bf16 v[82:85], v[176:179], v[200:203], v[82:85]
	v_mfma_f32_16x16x32_bf16 v[70:73], v[168:171], v[208:211], v[70:73]
	v_mfma_f32_16x16x32_bf16 v[66:69], v[176:179], v[208:211], v[66:69]
	v_mfma_f32_16x16x32_bf16 v[118:121], v[172:175], v[188:191], v[118:121]
	v_mfma_f32_16x16x32_bf16 v[114:117], v[180:183], v[188:191], v[114:117]
	v_mfma_f32_16x16x32_bf16 v[102:105], v[172:175], v[196:199], v[102:105]
	v_mfma_f32_16x16x32_bf16 v[98:101], v[180:183], v[196:199], v[98:101]
	v_mfma_f32_16x16x32_bf16 v[86:89], v[172:175], v[204:207], v[86:89]
	v_mfma_f32_16x16x32_bf16 v[82:85], v[180:183], v[204:207], v[82:85]
	v_mfma_f32_16x16x32_bf16 v[70:73], v[172:175], v[216:219], v[70:73]
	v_mfma_f32_16x16x32_bf16 v[66:69], v[180:183], v[216:219], v[66:69]
	s_barrier
	s_add_i32 s56, s56, s40
	v_lshl_add_u64 v[148:149], s[26:27], 0, v[130:131]
	s_mov_b32 m0, s56
	ds_read_b128 v[184:187], v154 offset:16384
	ds_read_b128 v[188:191], v154 offset:17408
	ds_read_b128 v[192:195], v154 offset:18432
	ds_read_b128 v[196:199], v154 offset:19456
	ds_read_b128 v[200:203], v154 offset:20480
	ds_read_b128 v[204:207], v154 offset:21504
	ds_read_b128 v[208:211], v154 offset:22528
	ds_read_b128 v[216:219], v154 offset:23552
	global_load_lds_dwordx4 v[148:149], off
	s_add_i32 m0, s56, 0x2000
	s_add_u32 s56, s26, 0x100000
	v_lshl_add_u64 v[212:213], s[26:27], 0, v[132:133]
	s_addc_u32 s57, s27, 0
	s_add_i32 s58, s58, s40
	global_load_lds_dwordx4 v[212:213], off
	v_lshl_add_u64 v[220:221], s[56:57], 0, v[130:131]
	s_mov_b32 m0, s58
	v_lshl_add_u64 v[222:223], s[28:29], 0, v[134:135]
	global_load_lds_dwordx4 v[220:221], off
	v_lshl_add_u64 v[220:221], s[56:57], 0, v[132:133]
	s_add_i32 m0, s58, 0x2000
	s_nop 0
	global_load_lds_dwordx4 v[220:221], off
	v_lshl_add_u64 v[220:221], s[28:29], 0, v[136:137]
	s_mov_b32 m0, s41
	s_nop 0
	global_load_lds_dwordx4 v[220:221], off
	s_mov_b32 m0, s44
	s_nop 0
	global_load_lds_dwordx4 v[222:223], off
	s_waitcnt vmcnt(8)
	s_waitcnt lgkmcnt(0)
	s_barrier
	s_waitcnt lgkmcnt(0)
	v_mfma_f32_16x16x32_bf16 v[62:65], v[144:147], v[184:187], v[62:65]
	v_mfma_f32_16x16x32_bf16 v[58:61], v[160:163], v[184:187], v[58:61]
	v_mfma_f32_16x16x32_bf16 v[46:49], v[144:147], v[192:195], v[46:49]
	v_mfma_f32_16x16x32_bf16 v[42:45], v[160:163], v[192:195], v[42:45]
	v_mfma_f32_16x16x32_bf16 v[30:33], v[144:147], v[200:203], v[30:33]
	v_mfma_f32_16x16x32_bf16 v[26:29], v[160:163], v[200:203], v[26:29]
	v_mfma_f32_16x16x32_bf16 v[14:17], v[144:147], v[208:211], v[14:17]
	v_mfma_f32_16x16x32_bf16 v[10:13], v[160:163], v[208:211], v[10:13]
	v_mfma_f32_16x16x32_bf16 v[62:65], v[156:159], v[188:191], v[62:65]
	v_mfma_f32_16x16x32_bf16 v[58:61], v[164:167], v[188:191], v[58:61]
	v_mfma_f32_16x16x32_bf16 v[46:49], v[156:159], v[196:199], v[46:49]
	v_mfma_f32_16x16x32_bf16 v[42:45], v[164:167], v[196:199], v[42:45]
	v_mfma_f32_16x16x32_bf16 v[30:33], v[156:159], v[204:207], v[30:33]
	v_mfma_f32_16x16x32_bf16 v[26:29], v[164:167], v[204:207], v[26:29]
	v_mfma_f32_16x16x32_bf16 v[14:17], v[156:159], v[216:219], v[14:17]
	v_mfma_f32_16x16x32_bf16 v[10:13], v[164:167], v[216:219], v[10:13]
	v_mfma_f32_16x16x32_bf16 v[54:57], v[168:171], v[184:187], v[54:57]
	v_mfma_f32_16x16x32_bf16 v[50:53], v[176:179], v[184:187], v[50:53]
	v_mfma_f32_16x16x32_bf16 v[38:41], v[168:171], v[192:195], v[38:41]
	v_mfma_f32_16x16x32_bf16 v[34:37], v[176:179], v[192:195], v[34:37]
	v_mfma_f32_16x16x32_bf16 v[22:25], v[168:171], v[200:203], v[22:25]
	v_mfma_f32_16x16x32_bf16 v[18:21], v[176:179], v[200:203], v[18:21]
	v_mfma_f32_16x16x32_bf16 v[6:9], v[168:171], v[208:211], v[6:9]
	v_mfma_f32_16x16x32_bf16 v[2:5], v[176:179], v[208:211], v[2:5]
	v_mfma_f32_16x16x32_bf16 v[54:57], v[172:175], v[188:191], v[54:57]
	v_mfma_f32_16x16x32_bf16 v[50:53], v[180:183], v[188:191], v[50:53]
	v_mfma_f32_16x16x32_bf16 v[38:41], v[172:175], v[196:199], v[38:41]
	v_mfma_f32_16x16x32_bf16 v[34:37], v[180:183], v[196:199], v[34:37]
	v_mfma_f32_16x16x32_bf16 v[22:25], v[172:175], v[204:207], v[22:25]
	v_mfma_f32_16x16x32_bf16 v[18:21], v[180:183], v[204:207], v[18:21]
	v_mfma_f32_16x16x32_bf16 v[6:9], v[172:175], v[216:219], v[6:9]
	v_mfma_f32_16x16x32_bf16 v[2:5], v[180:183], v[216:219], v[2:5]
	s_barrier
	s_add_i32 s56, 0, 0x18000
	v_add_u32_e32 v155, s56, v152
	s_add_i32 s57, 0, 0x1c000
	ds_read_b128 v[144:147], v155
	ds_read_b128 v[156:159], v155 offset:1024
	ds_read_b128 v[160:163], v155 offset:2048
	ds_read_b128 v[164:167], v155 offset:3072
	v_add_u32_e32 v155, s57, v152
	ds_read_b128 v[168:171], v155
	ds_read_b128 v[172:175], v155 offset:1024
	ds_read_b128 v[176:179], v155 offset:2048
	ds_read_b128 v[180:183], v155 offset:3072
	s_add_u32 s28, s28, 0x100000
	s_addc_u32 s29, s29, 0
	s_mov_b32 m0, s45
	v_lshl_add_u64 v[224:225], s[28:29], 0, v[136:137]
	ds_read_b128 v[184:187], v154 offset:32768
	ds_read_b128 v[188:191], v154 offset:33792
	ds_read_b128 v[192:195], v154 offset:34816
	ds_read_b128 v[196:199], v154 offset:35840
	ds_read_b128 v[200:203], v154 offset:36864
	ds_read_b128 v[204:207], v154 offset:37888
	ds_read_b128 v[208:211], v154 offset:38912
	ds_read_b128 v[216:219], v154 offset:39936
	global_load_lds_dwordx4 v[224:225], off
	v_lshl_add_u64 v[224:225], s[28:29], 0, v[134:135]
	s_mov_b32 m0, s46
	s_nop 0
	global_load_lds_dwordx4 v[224:225], off
	s_waitcnt vmcnt(8)
	s_waitcnt lgkmcnt(0)
	s_barrier
	s_waitcnt lgkmcnt(0)
	v_mfma_f32_16x16x32_bf16 v[126:129], v[144:147], v[184:187], v[126:129]
	v_mfma_f32_16x16x32_bf16 v[122:125], v[160:163], v[184:187], v[122:125]
	v_mfma_f32_16x16x32_bf16 v[110:113], v[144:147], v[192:195], v[110:113]
	v_mfma_f32_16x16x32_bf16 v[106:109], v[160:163], v[192:195], v[106:109]
	v_mfma_f32_16x16x32_bf16 v[94:97], v[144:147], v[200:203], v[94:97]
	v_mfma_f32_16x16x32_bf16 v[90:93], v[160:163], v[200:203], v[90:93]
	v_mfma_f32_16x16x32_bf16 v[78:81], v[144:147], v[208:211], v[78:81]
	v_mfma_f32_16x16x32_bf16 v[74:77], v[160:163], v[208:211], v[74:77]
	v_mfma_f32_16x16x32_bf16 v[126:129], v[156:159], v[188:191], v[126:129]
	v_mfma_f32_16x16x32_bf16 v[122:125], v[164:167], v[188:191], v[122:125]
	v_mfma_f32_16x16x32_bf16 v[110:113], v[156:159], v[196:199], v[110:113]
	v_mfma_f32_16x16x32_bf16 v[106:109], v[164:167], v[196:199], v[106:109]
	v_mfma_f32_16x16x32_bf16 v[94:97], v[156:159], v[204:207], v[94:97]
	v_mfma_f32_16x16x32_bf16 v[90:93], v[164:167], v[204:207], v[90:93]
	v_mfma_f32_16x16x32_bf16 v[78:81], v[156:159], v[216:219], v[78:81]
	v_mfma_f32_16x16x32_bf16 v[74:77], v[164:167], v[216:219], v[74:77]
	v_mfma_f32_16x16x32_bf16 v[118:121], v[168:171], v[184:187], v[118:121]
	v_mfma_f32_16x16x32_bf16 v[114:117], v[176:179], v[184:187], v[114:117]
	v_mfma_f32_16x16x32_bf16 v[102:105], v[168:171], v[192:195], v[102:105]
	v_mfma_f32_16x16x32_bf16 v[98:101], v[176:179], v[192:195], v[98:101]
	v_mfma_f32_16x16x32_bf16 v[86:89], v[168:171], v[200:203], v[86:89]
	v_mfma_f32_16x16x32_bf16 v[82:85], v[176:179], v[200:203], v[82:85]
	v_mfma_f32_16x16x32_bf16 v[70:73], v[168:171], v[208:211], v[70:73]
	v_mfma_f32_16x16x32_bf16 v[66:69], v[176:179], v[208:211], v[66:69]
	v_mfma_f32_16x16x32_bf16 v[118:121], v[172:175], v[188:191], v[118:121]
	v_mfma_f32_16x16x32_bf16 v[114:117], v[180:183], v[188:191], v[114:117]
	v_mfma_f32_16x16x32_bf16 v[102:105], v[172:175], v[196:199], v[102:105]
	v_mfma_f32_16x16x32_bf16 v[98:101], v[180:183], v[196:199], v[98:101]
	v_mfma_f32_16x16x32_bf16 v[86:89], v[172:175], v[204:207], v[86:89]
	v_mfma_f32_16x16x32_bf16 v[82:85], v[180:183], v[204:207], v[82:85]
	v_mfma_f32_16x16x32_bf16 v[70:73], v[172:175], v[216:219], v[70:73]
	v_mfma_f32_16x16x32_bf16 v[66:69], v[180:183], v[216:219], v[66:69]
	s_barrier
	s_add_i32 s28, s56, s40
	v_lshl_add_u64 v[148:149], v[148:149], 0, s[18:19]
	s_mov_b32 m0, s28
	ds_read_b128 v[184:187], v154 offset:49152
	ds_read_b128 v[188:191], v154 offset:50176
	ds_read_b128 v[192:195], v154 offset:51200
	ds_read_b128 v[196:199], v154 offset:52224
	ds_read_b128 v[200:203], v154 offset:53248
	ds_read_b128 v[204:207], v154 offset:54272
	ds_read_b128 v[208:211], v154 offset:55296
	ds_read_b128 v[216:219], v154 offset:56320
	global_load_lds_dwordx4 v[148:149], off
	s_add_i32 m0, s28, 0x2000
	s_add_u32 s26, s26, 0x100080
	v_lshl_add_u64 v[148:149], v[212:213], 0, s[18:19]
	s_addc_u32 s27, s27, 0
	s_add_i32 s28, s57, s40
	global_load_lds_dwordx4 v[148:149], off
	v_lshl_add_u64 v[148:149], s[26:27], 0, v[130:131]
	s_mov_b32 m0, s28
	s_nop 0
	global_load_lds_dwordx4 v[148:149], off
	v_lshl_add_u64 v[148:149], s[26:27], 0, v[132:133]
	s_add_i32 m0, s28, 0x2000
	s_nop 0
	global_load_lds_dwordx4 v[148:149], off
	v_lshl_add_u64 v[148:149], v[220:221], 0, s[18:19]
	s_mov_b32 m0, s30
	s_nop 0
	global_load_lds_dwordx4 v[148:149], off
	v_lshl_add_u64 v[148:149], v[222:223], 0, s[18:19]
	s_mov_b32 m0, s47
	s_nop 0
	global_load_lds_dwordx4 v[148:149], off
	s_waitcnt vmcnt(8)
	s_waitcnt lgkmcnt(0)
	s_barrier
	s_waitcnt lgkmcnt(0)
	v_mfma_f32_16x16x32_bf16 v[62:65], v[144:147], v[184:187], v[62:65]
	v_mfma_f32_16x16x32_bf16 v[58:61], v[160:163], v[184:187], v[58:61]
	v_mfma_f32_16x16x32_bf16 v[46:49], v[144:147], v[192:195], v[46:49]
	v_mfma_f32_16x16x32_bf16 v[42:45], v[160:163], v[192:195], v[42:45]
	v_mfma_f32_16x16x32_bf16 v[30:33], v[144:147], v[200:203], v[30:33]
	v_mfma_f32_16x16x32_bf16 v[26:29], v[160:163], v[200:203], v[26:29]
	v_mfma_f32_16x16x32_bf16 v[14:17], v[144:147], v[208:211], v[14:17]
	v_mfma_f32_16x16x32_bf16 v[10:13], v[160:163], v[208:211], v[10:13]
	v_mfma_f32_16x16x32_bf16 v[62:65], v[156:159], v[188:191], v[62:65]
	v_mfma_f32_16x16x32_bf16 v[58:61], v[164:167], v[188:191], v[58:61]
	v_mfma_f32_16x16x32_bf16 v[46:49], v[156:159], v[196:199], v[46:49]
	v_mfma_f32_16x16x32_bf16 v[42:45], v[164:167], v[196:199], v[42:45]
	v_mfma_f32_16x16x32_bf16 v[30:33], v[156:159], v[204:207], v[30:33]
	v_mfma_f32_16x16x32_bf16 v[26:29], v[164:167], v[204:207], v[26:29]
	v_mfma_f32_16x16x32_bf16 v[14:17], v[156:159], v[216:219], v[14:17]
	v_mfma_f32_16x16x32_bf16 v[10:13], v[164:167], v[216:219], v[10:13]
	v_mfma_f32_16x16x32_bf16 v[54:57], v[168:171], v[184:187], v[54:57]
	v_mfma_f32_16x16x32_bf16 v[50:53], v[176:179], v[184:187], v[50:53]
	v_mfma_f32_16x16x32_bf16 v[38:41], v[168:171], v[192:195], v[38:41]
	v_mfma_f32_16x16x32_bf16 v[34:37], v[176:179], v[192:195], v[34:37]
	v_mfma_f32_16x16x32_bf16 v[22:25], v[168:171], v[200:203], v[22:25]
	v_mfma_f32_16x16x32_bf16 v[18:21], v[176:179], v[200:203], v[18:21]
	v_mfma_f32_16x16x32_bf16 v[6:9], v[168:171], v[208:211], v[6:9]
	v_mfma_f32_16x16x32_bf16 v[2:5], v[176:179], v[208:211], v[2:5]
	v_mfma_f32_16x16x32_bf16 v[54:57], v[172:175], v[188:191], v[54:57]
	v_mfma_f32_16x16x32_bf16 v[50:53], v[180:183], v[188:191], v[50:53]
	v_mfma_f32_16x16x32_bf16 v[38:41], v[172:175], v[196:199], v[38:41]
	v_mfma_f32_16x16x32_bf16 v[34:37], v[180:183], v[196:199], v[34:37]
	v_mfma_f32_16x16x32_bf16 v[22:25], v[172:175], v[204:207], v[22:25]
	v_mfma_f32_16x16x32_bf16 v[18:21], v[180:183], v[204:207], v[18:21]
	v_mfma_f32_16x16x32_bf16 v[6:9], v[172:175], v[216:219], v[6:9]
	v_mfma_f32_16x16x32_bf16 v[2:5], v[180:183], v[216:219], v[2:5]
	s_barrier
	s_add_i32 s55, s55, 2
	s_add_u32 s24, s24, 0x100
	s_addc_u32 s25, s25, 0
	s_add_u32 s53, s53, 0x100
	s_addc_u32 s54, s54, 0
	s_cmp_gt_u32 s55, 61
	s_cbranch_scc0 .LBB0_872
	s_setprio 0
	s_and_b64 vcc, exec, s[6:7]
	s_cbranch_vccz .LBB0_875
	s_barrier

.LBB0_1023:
	s_ashr_i32 s53, s52, 31
	s_lshl_b64 s[54:55], s[52:53], 21
	s_add_u32 s54, s60, s54
	s_addc_u32 s55, s61, s55
	s_and_b64 s[56:57], s[44:45], exec
	s_cselect_b32 s30, s55, s3
	s_cselect_b32 s53, s54, s2
	s_ashr_i32 s51, s50, 31
	s_lshl_b64 s[56:57], s[50:51], 21
	s_add_u32 s56, s62, s56
	s_addc_u32 s57, s63, s57
	s_and_b64 s[58:59], s[44:45], exec
	s_cselect_b32 s51, s57, s47
	s_cselect_b32 s79, s56, s46
	s_add_u32 s2, s2, 0x100080
	s_addc_u32 s3, s3, 0
	s_add_u32 s80, s46, 0x100
	v_mov_b32_e32 v2, 0
	s_addc_u32 s81, s47, 0
	s_mov_b32 s82, -2
	v_mov_b32_e32 v3, v2
	v_mov_b32_e32 v4, v2
	v_mov_b32_e32 v5, v2
	v_mov_b32_e32 v10, v2
	v_mov_b32_e32 v11, v2
	v_mov_b32_e32 v12, v2
	v_mov_b32_e32 v13, v2
	s_waitcnt vmcnt(0)
	v_mov_b32_e32 v18, v2
	v_mov_b32_e32 v19, v2
	v_mov_b32_e32 v20, v2
	v_mov_b32_e32 v21, v2
	v_mov_b32_e32 v26, v2
	v_mov_b32_e32 v27, v2
	v_mov_b32_e32 v28, v2
	v_mov_b32_e32 v29, v2
	v_mov_b32_e32 v34, v2
	v_mov_b32_e32 v35, v2
	v_mov_b32_e32 v36, v2
	v_mov_b32_e32 v37, v2
	v_mov_b32_e32 v42, v2
	v_mov_b32_e32 v43, v2
	v_mov_b32_e32 v44, v2
	v_mov_b32_e32 v45, v2
	v_mov_b32_e32 v50, v2
	v_mov_b32_e32 v51, v2
	v_mov_b32_e32 v52, v2
	v_mov_b32_e32 v53, v2
	v_mov_b32_e32 v58, v2
	v_mov_b32_e32 v59, v2
	v_mov_b32_e32 v60, v2
	v_mov_b32_e32 v61, v2
	v_mov_b32_e32 v6, v2
	v_mov_b32_e32 v7, v2
	v_mov_b32_e32 v8, v2
	v_mov_b32_e32 v9, v2
	v_mov_b32_e32 v14, v2
	v_mov_b32_e32 v15, v2
	v_mov_b32_e32 v16, v2
	v_mov_b32_e32 v17, v2
	v_mov_b32_e32 v22, v2
	v_mov_b32_e32 v23, v2
	v_mov_b32_e32 v24, v2
	v_mov_b32_e32 v25, v2
	v_mov_b32_e32 v30, v2
	v_mov_b32_e32 v31, v2
	v_mov_b32_e32 v32, v2
	v_mov_b32_e32 v33, v2
	v_mov_b32_e32 v38, v2
	v_mov_b32_e32 v39, v2
	v_mov_b32_e32 v40, v2
	v_mov_b32_e32 v41, v2
	v_mov_b32_e32 v46, v2
	v_mov_b32_e32 v47, v2
	v_mov_b32_e32 v48, v2
	v_mov_b32_e32 v49, v2
	v_mov_b32_e32 v54, v2
	v_mov_b32_e32 v55, v2
	v_mov_b32_e32 v56, v2
	v_mov_b32_e32 v57, v2
	v_mov_b32_e32 v86, v2
	v_mov_b32_e32 v87, v2
	v_mov_b32_e32 v88, v2
	v_mov_b32_e32 v89, v2
	v_mov_b32_e32 v114, v2
	v_mov_b32_e32 v115, v2
	v_mov_b32_e32 v116, v2
	v_mov_b32_e32 v117, v2
	v_mov_b32_e32 v122, v2
	v_mov_b32_e32 v123, v2
	v_mov_b32_e32 v124, v2
	v_mov_b32_e32 v125, v2
	v_mov_b32_e32 v132, v2
	v_mov_b32_e32 v133, v2
	v_mov_b32_e32 v134, v2
	v_mov_b32_e32 v135, v2
	v_mov_b32_e32 v140, v2
	v_mov_b32_e32 v141, v2
	v_mov_b32_e32 v142, v2
	v_mov_b32_e32 v143, v2
	v_mov_b32_e32 v148, v2
	v_mov_b32_e32 v149, v2
	v_mov_b32_e32 v150, v2
	v_mov_b32_e32 v151, v2
	v_mov_b32_e32 v156, v2
	v_mov_b32_e32 v157, v2
	v_mov_b32_e32 v158, v2
	v_mov_b32_e32 v159, v2
	v_mov_b32_e32 v164, v2
	v_mov_b32_e32 v165, v2
	v_mov_b32_e32 v166, v2
	v_mov_b32_e32 v167, v2
	v_mov_b32_e32 v172, v2
	v_mov_b32_e32 v173, v2
	v_mov_b32_e32 v174, v2
	v_mov_b32_e32 v175, v2
	v_mov_b32_e32 v118, v2
	v_mov_b32_e32 v119, v2
	v_mov_b32_e32 v120, v2
	v_mov_b32_e32 v121, v2
	v_mov_b32_e32 v126, v2
	v_mov_b32_e32 v127, v2
	v_mov_b32_e32 v128, v2
	v_mov_b32_e32 v129, v2
	v_mov_b32_e32 v136, v2
	v_mov_b32_e32 v137, v2
	v_mov_b32_e32 v138, v2
	v_mov_b32_e32 v139, v2
	v_mov_b32_e32 v144, v2
	v_mov_b32_e32 v145, v2
	v_mov_b32_e32 v146, v2
	v_mov_b32_e32 v147, v2
	v_mov_b32_e32 v152, v2
	v_mov_b32_e32 v153, v2
	v_mov_b32_e32 v154, v2
	v_mov_b32_e32 v155, v2
	v_mov_b32_e32 v160, v2
	v_mov_b32_e32 v161, v2
	v_mov_b32_e32 v162, v2
	v_mov_b32_e32 v163, v2
	v_mov_b32_e32 v168, v2
	v_mov_b32_e32 v169, v2
	v_mov_b32_e32 v170, v2
	v_mov_b32_e32 v171, v2
	v_mov_b32_e32 v176, v2
	v_mov_b32_e32 v177, v2
	v_mov_b32_e32 v178, v2
	v_mov_b32_e32 v179, v2
	v_readfirstlane_b32 s100, v0
	s_cmp_lt_u32 s100, 0x100
	s_cbranch_scc1 .Lprio_skip_1024
	s_setprio 1
.Lprio_skip_1024:
.LBB0_1024:
	s_add_u32 s46, s2, 0xfff00080
	s_addc_u32 s47, s3, -1
	s_add_i32 s83, 0, 0x10000
	s_cmp_eq_u32 s82, 60
	s_cselect_b32 s59, s30, s47
	s_cselect_b32 s58, s53, s46
	s_cselect_b32 s47, s51, s81
	s_cselect_b32 s46, s79, s80
	s_add_i32 s86, 0, 0x14000
	v_add_u32_e32 v74, s83, v244
	v_add_u32_e32 v94, s86, v244
	ds_read_b128 v[62:65], v74
	ds_read_b128 v[66:69], v74 offset:1024
	ds_read_b128 v[70:73], v74 offset:2048
	ds_read_b128 v[74:77], v74 offset:3072
	ds_read_b128 v[78:81], v94
	ds_read_b128 v[82:85], v94 offset:1024
	ds_read_b128 v[90:93], v94 offset:2048
	ds_read_b128 v[94:97], v94 offset:3072
	v_lshl_add_u64 v[196:197], s[2:3], 0, v[222:223]
	s_add_i32 m0, s67, 0xc000
	ds_read_b128 v[98:101], v250
	ds_read_b128 v[102:105], v250 offset:1024
	ds_read_b128 v[106:109], v250 offset:2048
	ds_read_b128 v[110:113], v250 offset:3072
	ds_read_b128 v[180:183], v250 offset:4096
	ds_read_b128 v[184:187], v250 offset:5120
	ds_read_b128 v[188:191], v250 offset:6144
	ds_read_b128 v[192:195], v250 offset:7168
	global_load_lds_dwordx4 v[196:197], off
	v_lshl_add_u64 v[196:197], s[2:3], 0, v[224:225]
	s_add_i32 m0, s67, 0xe000
	s_nop 0
	global_load_lds_dwordx4 v[196:197], off
	s_waitcnt vmcnt(8)
	s_waitcnt lgkmcnt(0)
	s_barrier
	s_waitcnt lgkmcnt(0)
	v_mfma_f32_16x16x32_bf16 v[176:179], v[62:65], v[98:101], v[176:179]
	v_mfma_f32_16x16x32_bf16 v[168:171], v[70:73], v[98:101], v[168:171]
	v_mfma_f32_16x16x32_bf16 v[160:163], v[62:65], v[106:109], v[160:163]
	v_mfma_f32_16x16x32_bf16 v[152:155], v[70:73], v[106:109], v[152:155]
	v_mfma_f32_16x16x32_bf16 v[144:147], v[62:65], v[180:183], v[144:147]
	v_mfma_f32_16x16x32_bf16 v[136:139], v[70:73], v[180:183], v[136:139]
	v_mfma_f32_16x16x32_bf16 v[126:129], v[62:65], v[188:191], v[126:129]
	v_mfma_f32_16x16x32_bf16 v[118:121], v[70:73], v[188:191], v[118:121]
	v_mfma_f32_16x16x32_bf16 v[176:179], v[66:69], v[102:105], v[176:179]
	v_mfma_f32_16x16x32_bf16 v[168:171], v[74:77], v[102:105], v[168:171]
	v_mfma_f32_16x16x32_bf16 v[160:163], v[66:69], v[110:113], v[160:163]
	v_mfma_f32_16x16x32_bf16 v[152:155], v[74:77], v[110:113], v[152:155]
	v_mfma_f32_16x16x32_bf16 v[144:147], v[66:69], v[184:187], v[144:147]
	v_mfma_f32_16x16x32_bf16 v[136:139], v[74:77], v[184:187], v[136:139]
	v_mfma_f32_16x16x32_bf16 v[126:129], v[66:69], v[192:195], v[126:129]
	v_mfma_f32_16x16x32_bf16 v[118:121], v[74:77], v[192:195], v[118:121]
	v_mfma_f32_16x16x32_bf16 v[172:175], v[78:81], v[98:101], v[172:175]
	v_mfma_f32_16x16x32_bf16 v[98:101], v[90:93], v[98:101], v[164:167]
	v_mfma_f32_16x16x32_bf16 v[172:175], v[82:85], v[102:105], v[172:175]
	v_mfma_f32_16x16x32_bf16 v[98:101], v[94:97], v[102:105], v[98:101]
	v_mfma_f32_16x16x32_bf16 v[102:105], v[78:81], v[106:109], v[156:159]
	v_mfma_f32_16x16x32_bf16 v[106:109], v[90:93], v[106:109], v[148:151]
	v_mfma_f32_16x16x32_bf16 v[132:135], v[90:93], v[180:183], v[132:135]
	v_mfma_f32_16x16x32_bf16 v[122:125], v[78:81], v[188:191], v[122:125]
	v_mfma_f32_16x16x32_bf16 v[114:117], v[90:93], v[188:191], v[114:117]
	v_mfma_f32_16x16x32_bf16 v[102:105], v[82:85], v[110:113], v[102:105]
	v_mfma_f32_16x16x32_bf16 v[106:109], v[94:97], v[110:113], v[106:109]
	v_mfma_f32_16x16x32_bf16 v[110:113], v[78:81], v[180:183], v[140:143]
	v_mfma_f32_16x16x32_bf16 v[132:135], v[94:97], v[184:187], v[132:135]
	v_mfma_f32_16x16x32_bf16 v[122:125], v[82:85], v[192:195], v[122:125]
	v_mfma_f32_16x16x32_bf16 v[114:117], v[94:97], v[192:195], v[114:117]
	v_mfma_f32_16x16x32_bf16 v[110:113], v[82:85], v[184:187], v[110:113]
	s_barrier
	s_add_i32 s83, s83, s66
	v_lshl_add_u64 v[204:205], s[46:47], 0, v[130:131]
	s_mov_b32 m0, s83
	ds_read_b128 v[140:143], v250 offset:16384
	ds_read_b128 v[148:151], v250 offset:17408
	ds_read_b128 v[156:159], v250 offset:18432
	ds_read_b128 v[164:167], v250 offset:19456
	ds_read_b128 v[180:183], v250 offset:20480
	ds_read_b128 v[184:187], v250 offset:21504
	ds_read_b128 v[188:191], v250 offset:22528
	ds_read_b128 v[192:195], v250 offset:23552
	global_load_lds_dwordx4 v[204:205], off
	s_add_i32 m0, s83, 0x2000
	s_add_u32 s84, s46, 0x100000
	v_lshl_add_u64 v[206:207], s[46:47], 0, v[216:217]
	s_addc_u32 s85, s47, 0
	s_add_i32 s83, s86, s66
	global_load_lds_dwordx4 v[206:207], off
	v_lshl_add_u64 v[196:197], s[84:85], 0, v[130:131]
	s_mov_b32 m0, s83
	v_lshl_add_u64 v[208:209], s[58:59], 0, v[220:221]
	global_load_lds_dwordx4 v[196:197], off
	v_lshl_add_u64 v[196:197], s[84:85], 0, v[216:217]
	s_add_i32 m0, s83, 0x2000
	v_lshl_add_u64 v[210:211], s[58:59], 0, v[218:219]
	global_load_lds_dwordx4 v[196:197], off
	s_mov_b32 m0, s67
	s_nop 0
	global_load_lds_dwordx4 v[208:209], off
	s_mov_b32 m0, s68
	s_nop 0
	global_load_lds_dwordx4 v[210:211], off
	s_waitcnt vmcnt(8)
	s_waitcnt lgkmcnt(0)
	s_barrier
	s_waitcnt lgkmcnt(0)
	v_mfma_f32_16x16x32_bf16 v[86:89], v[62:65], v[140:143], v[86:89]
	v_mfma_f32_16x16x32_bf16 v[54:57], v[70:73], v[140:143], v[54:57]
	v_mfma_f32_16x16x32_bf16 v[46:49], v[62:65], v[156:159], v[46:49]
	v_mfma_f32_16x16x32_bf16 v[38:41], v[70:73], v[156:159], v[38:41]
	v_mfma_f32_16x16x32_bf16 v[30:33], v[62:65], v[180:183], v[30:33]
	v_mfma_f32_16x16x32_bf16 v[22:25], v[70:73], v[180:183], v[22:25]
	v_mfma_f32_16x16x32_bf16 v[14:17], v[62:65], v[188:191], v[14:17]
	v_mfma_f32_16x16x32_bf16 v[6:9], v[70:73], v[188:191], v[6:9]
	v_mfma_f32_16x16x32_bf16 v[86:89], v[66:69], v[148:151], v[86:89]
	v_mfma_f32_16x16x32_bf16 v[54:57], v[74:77], v[148:151], v[54:57]
	v_mfma_f32_16x16x32_bf16 v[46:49], v[66:69], v[164:167], v[46:49]
	v_mfma_f32_16x16x32_bf16 v[38:41], v[74:77], v[164:167], v[38:41]
	v_mfma_f32_16x16x32_bf16 v[30:33], v[66:69], v[184:187], v[30:33]
	v_mfma_f32_16x16x32_bf16 v[22:25], v[74:77], v[184:187], v[22:25]
	v_mfma_f32_16x16x32_bf16 v[14:17], v[66:69], v[192:195], v[14:17]
	v_mfma_f32_16x16x32_bf16 v[6:9], v[74:77], v[192:195], v[6:9]
	v_mfma_f32_16x16x32_bf16 v[58:61], v[78:81], v[140:143], v[58:61]
	v_mfma_f32_16x16x32_bf16 v[50:53], v[90:93], v[140:143], v[50:53]
	v_mfma_f32_16x16x32_bf16 v[42:45], v[78:81], v[156:159], v[42:45]
	v_mfma_f32_16x16x32_bf16 v[34:37], v[90:93], v[156:159], v[34:37]
	v_mfma_f32_16x16x32_bf16 v[26:29], v[78:81], v[180:183], v[26:29]
	v_mfma_f32_16x16x32_bf16 v[18:21], v[90:93], v[180:183], v[18:21]
	v_mfma_f32_16x16x32_bf16 v[10:13], v[78:81], v[188:191], v[10:13]
	v_mfma_f32_16x16x32_bf16 v[2:5], v[90:93], v[188:191], v[2:5]
	v_mfma_f32_16x16x32_bf16 v[58:61], v[82:85], v[148:151], v[58:61]
	v_mfma_f32_16x16x32_bf16 v[50:53], v[94:97], v[148:151], v[50:53]
	v_mfma_f32_16x16x32_bf16 v[42:45], v[82:85], v[164:167], v[42:45]
	v_mfma_f32_16x16x32_bf16 v[34:37], v[94:97], v[164:167], v[34:37]
	v_mfma_f32_16x16x32_bf16 v[26:29], v[82:85], v[184:187], v[26:29]
	v_mfma_f32_16x16x32_bf16 v[18:21], v[94:97], v[184:187], v[18:21]
	v_mfma_f32_16x16x32_bf16 v[10:13], v[82:85], v[192:195], v[10:13]
	v_mfma_f32_16x16x32_bf16 v[2:5], v[94:97], v[192:195], v[2:5]
	s_barrier
	s_add_i32 s83, 0, 0x18000
	s_add_i32 s84, 0, 0x1c000
	v_add_u32_e32 v74, s83, v244
	v_add_u32_e32 v94, s84, v244
	ds_read_b128 v[62:65], v74
	ds_read_b128 v[66:69], v74 offset:1024
	ds_read_b128 v[70:73], v74 offset:2048
	ds_read_b128 v[74:77], v74 offset:3072
	ds_read_b128 v[78:81], v94
	ds_read_b128 v[82:85], v94 offset:1024
	ds_read_b128 v[90:93], v94 offset:2048
	ds_read_b128 v[94:97], v94 offset:3072
	s_add_u32 s58, s58, 0x100000
	s_addc_u32 s59, s59, 0
	s_mov_b32 m0, s69
	v_lshl_add_u64 v[156:157], s[58:59], 0, v[220:221]
	ds_read_b128 v[140:143], v250 offset:32768
	ds_read_b128 v[148:151], v250 offset:33792
	ds_read_b128 v[180:183], v250 offset:34816
	ds_read_b128 v[184:187], v250 offset:35840
	ds_read_b128 v[188:191], v250 offset:36864
	ds_read_b128 v[192:195], v250 offset:37888
	ds_read_b128 v[196:199], v250 offset:38912
	ds_read_b128 v[200:203], v250 offset:39936
	global_load_lds_dwordx4 v[156:157], off
	v_lshl_add_u64 v[156:157], s[58:59], 0, v[218:219]
	s_mov_b32 m0, s70
	s_nop 0
	global_load_lds_dwordx4 v[156:157], off
	s_waitcnt vmcnt(8)
	s_waitcnt lgkmcnt(0)
	s_barrier
	s_waitcnt lgkmcnt(0)
	v_mfma_f32_16x16x32_bf16 v[156:159], v[62:65], v[140:143], v[176:179]
	v_mfma_f32_16x16x32_bf16 v[176:179], v[66:69], v[148:151], v[156:159]
	v_mfma_f32_16x16x32_bf16 v[156:159], v[70:73], v[140:143], v[168:171]
	v_mfma_f32_16x16x32_bf16 v[168:171], v[74:77], v[148:151], v[156:159]
	v_mfma_f32_16x16x32_bf16 v[156:159], v[62:65], v[180:183], v[160:163]
	v_mfma_f32_16x16x32_bf16 v[152:155], v[70:73], v[180:183], v[152:155]
	v_mfma_f32_16x16x32_bf16 v[144:147], v[62:65], v[188:191], v[144:147]
	v_mfma_f32_16x16x32_bf16 v[136:139], v[70:73], v[188:191], v[136:139]
	v_mfma_f32_16x16x32_bf16 v[126:129], v[62:65], v[196:199], v[126:129]
	v_mfma_f32_16x16x32_bf16 v[118:121], v[70:73], v[196:199], v[118:121]
	v_mfma_f32_16x16x32_bf16 v[160:163], v[66:69], v[184:187], v[156:159]
	v_mfma_f32_16x16x32_bf16 v[152:155], v[74:77], v[184:187], v[152:155]
	v_mfma_f32_16x16x32_bf16 v[144:147], v[66:69], v[192:195], v[144:147]
	v_mfma_f32_16x16x32_bf16 v[136:139], v[74:77], v[192:195], v[136:139]
	v_mfma_f32_16x16x32_bf16 v[126:129], v[66:69], v[200:203], v[126:129]
	v_mfma_f32_16x16x32_bf16 v[118:121], v[74:77], v[200:203], v[118:121]
	v_mfma_f32_16x16x32_bf16 v[98:101], v[90:93], v[140:143], v[98:101]
	v_mfma_f32_16x16x32_bf16 v[156:159], v[78:81], v[140:143], v[172:175]
	v_mfma_f32_16x16x32_bf16 v[164:167], v[94:97], v[148:151], v[98:101]
	v_mfma_f32_16x16x32_bf16 v[98:101], v[78:81], v[180:183], v[102:105]
	v_mfma_f32_16x16x32_bf16 v[172:175], v[82:85], v[148:151], v[156:159]
	v_mfma_f32_16x16x32_bf16 v[156:159], v[82:85], v[184:187], v[98:101]
	v_mfma_f32_16x16x32_bf16 v[98:101], v[90:93], v[180:183], v[106:109]
	v_mfma_f32_16x16x32_bf16 v[148:151], v[94:97], v[184:187], v[98:101]
	v_mfma_f32_16x16x32_bf16 v[98:101], v[78:81], v[188:191], v[110:113]
	v_mfma_f32_16x16x32_bf16 v[140:143], v[82:85], v[192:195], v[98:101]
	v_mfma_f32_16x16x32_bf16 v[98:101], v[90:93], v[188:191], v[132:135]
	v_mfma_f32_16x16x32_bf16 v[132:135], v[94:97], v[192:195], v[98:101]
	v_mfma_f32_16x16x32_bf16 v[98:101], v[78:81], v[196:199], v[122:125]
	v_mfma_f32_16x16x32_bf16 v[122:125], v[82:85], v[200:203], v[98:101]
	v_mfma_f32_16x16x32_bf16 v[98:101], v[90:93], v[196:199], v[114:117]
	v_mfma_f32_16x16x32_bf16 v[114:117], v[94:97], v[200:203], v[98:101]
	s_barrier
	s_add_i32 s58, s83, s66
	v_lshl_add_u64 v[196:197], v[204:205], 0, s[18:19]
	s_mov_b32 m0, s58
	s_nop 1
	ds_read_b128 v[98:101], v250 offset:49152
	ds_read_b128 v[102:105], v250 offset:50176
	ds_read_b128 v[106:109], v250 offset:51200
	ds_read_b128 v[110:113], v250 offset:52224
	ds_read_b128 v[180:183], v250 offset:53248
	ds_read_b128 v[184:187], v250 offset:54272
	ds_read_b128 v[188:191], v250 offset:55296
	ds_read_b128 v[192:195], v250 offset:56320
	global_load_lds_dwordx4 v[196:197], off
	s_add_i32 m0, s58, 0x2000
	s_add_u32 s46, s46, 0x100080
	v_lshl_add_u64 v[196:197], v[206:207], 0, s[18:19]
	s_addc_u32 s47, s47, 0
	s_add_i32 s58, s84, s66
	global_load_lds_dwordx4 v[196:197], off
	v_lshl_add_u64 v[196:197], s[46:47], 0, v[130:131]
	s_mov_b32 m0, s58
	s_nop 0
	global_load_lds_dwordx4 v[196:197], off
	v_lshl_add_u64 v[196:197], s[46:47], 0, v[216:217]
	s_add_i32 m0, s58, 0x2000
	s_nop 0
	global_load_lds_dwordx4 v[196:197], off
	v_lshl_add_u64 v[196:197], v[208:209], 0, s[18:19]
	s_mov_b32 m0, s74
	s_nop 0
	global_load_lds_dwordx4 v[196:197], off
	v_lshl_add_u64 v[196:197], v[210:211], 0, s[18:19]
	s_mov_b32 m0, s75
	s_nop 0
	global_load_lds_dwordx4 v[196:197], off
	s_waitcnt vmcnt(8)
	s_waitcnt lgkmcnt(0)
	s_barrier
	s_waitcnt lgkmcnt(0)
	v_mfma_f32_16x16x32_bf16 v[86:89], v[62:65], v[98:101], v[86:89]
	v_mfma_f32_16x16x32_bf16 v[54:57], v[70:73], v[98:101], v[54:57]
	v_mfma_f32_16x16x32_bf16 v[46:49], v[62:65], v[106:109], v[46:49]
	v_mfma_f32_16x16x32_bf16 v[38:41], v[70:73], v[106:109], v[38:41]
	v_mfma_f32_16x16x32_bf16 v[30:33], v[62:65], v[180:183], v[30:33]
	v_mfma_f32_16x16x32_bf16 v[22:25], v[70:73], v[180:183], v[22:25]
	v_mfma_f32_16x16x32_bf16 v[14:17], v[62:65], v[188:191], v[14:17]
	v_mfma_f32_16x16x32_bf16 v[6:9], v[70:73], v[188:191], v[6:9]
	v_mfma_f32_16x16x32_bf16 v[86:89], v[66:69], v[102:105], v[86:89]
	v_mfma_f32_16x16x32_bf16 v[54:57], v[74:77], v[102:105], v[54:57]
	v_mfma_f32_16x16x32_bf16 v[46:49], v[66:69], v[110:113], v[46:49]
	v_mfma_f32_16x16x32_bf16 v[38:41], v[74:77], v[110:113], v[38:41]
	v_mfma_f32_16x16x32_bf16 v[30:33], v[66:69], v[184:187], v[30:33]
	v_mfma_f32_16x16x32_bf16 v[22:25], v[74:77], v[184:187], v[22:25]
	v_mfma_f32_16x16x32_bf16 v[14:17], v[66:69], v[192:195], v[14:17]
	v_mfma_f32_16x16x32_bf16 v[6:9], v[74:77], v[192:195], v[6:9]
	v_mfma_f32_16x16x32_bf16 v[58:61], v[78:81], v[98:101], v[58:61]
	v_mfma_f32_16x16x32_bf16 v[50:53], v[90:93], v[98:101], v[50:53]
	v_mfma_f32_16x16x32_bf16 v[42:45], v[78:81], v[106:109], v[42:45]
	v_mfma_f32_16x16x32_bf16 v[34:37], v[90:93], v[106:109], v[34:37]
	v_mfma_f32_16x16x32_bf16 v[26:29], v[78:81], v[180:183], v[26:29]
	v_mfma_f32_16x16x32_bf16 v[18:21], v[90:93], v[180:183], v[18:21]
	v_mfma_f32_16x16x32_bf16 v[10:13], v[78:81], v[188:191], v[10:13]
	v_mfma_f32_16x16x32_bf16 v[2:5], v[90:93], v[188:191], v[2:5]
	v_mfma_f32_16x16x32_bf16 v[58:61], v[82:85], v[102:105], v[58:61]
	v_mfma_f32_16x16x32_bf16 v[50:53], v[94:97], v[102:105], v[50:53]
	v_mfma_f32_16x16x32_bf16 v[42:45], v[82:85], v[110:113], v[42:45]
	v_mfma_f32_16x16x32_bf16 v[34:37], v[94:97], v[110:113], v[34:37]
	v_mfma_f32_16x16x32_bf16 v[26:29], v[82:85], v[184:187], v[26:29]
	v_mfma_f32_16x16x32_bf16 v[18:21], v[94:97], v[184:187], v[18:21]
	v_mfma_f32_16x16x32_bf16 v[10:13], v[82:85], v[192:195], v[10:13]
	v_mfma_f32_16x16x32_bf16 v[2:5], v[94:97], v[192:195], v[2:5]
	s_barrier
	s_add_i32 s82, s82, 2
	s_add_u32 s2, s2, 0x100
	s_addc_u32 s3, s3, 0
	s_add_u32 s80, s80, 0x100
	s_addc_u32 s81, s81, 0
	s_cmp_gt_u32 s82, 61
	s_cbranch_scc0 .LBB0_1024
	s_setprio 0
	v_mov_b64_e32 v[214:215], 0x400
	s_and_b64 vcc, exec, s[16:17]
	s_cbranch_vccz .LBB0_1027
	s_barrier

.LBB0_1327:
	s_add_u32 s54, s24, 0x100
	v_mov_b32_e32 v2, 0
	s_addc_u32 s55, s25, 0
	s_mov_b32 s56, -2
	v_mov_b32_e32 v3, v2
	v_mov_b32_e32 v4, v2
	v_mov_b32_e32 v5, v2
	v_mov_b32_e32 v6, v2
	v_mov_b32_e32 v7, v2
	v_mov_b32_e32 v8, v2
	v_mov_b32_e32 v9, v2
	v_mov_b32_e32 v18, v2
	v_mov_b32_e32 v19, v2
	v_mov_b32_e32 v20, v2
	v_mov_b32_e32 v21, v2
	v_mov_b32_e32 v22, v2
	v_mov_b32_e32 v23, v2
	v_mov_b32_e32 v24, v2
	v_mov_b32_e32 v25, v2
	s_waitcnt vmcnt(0)
	v_mov_b32_e32 v34, v2
	v_mov_b32_e32 v35, v2
	v_mov_b32_e32 v36, v2
	v_mov_b32_e32 v37, v2
	v_mov_b32_e32 v38, v2
	v_mov_b32_e32 v39, v2
	v_mov_b32_e32 v40, v2
	v_mov_b32_e32 v41, v2
	v_mov_b32_e32 v50, v2
	v_mov_b32_e32 v51, v2
	v_mov_b32_e32 v52, v2
	v_mov_b32_e32 v53, v2
	v_mov_b32_e32 v54, v2
	v_mov_b32_e32 v55, v2
	v_mov_b32_e32 v56, v2
	v_mov_b32_e32 v57, v2
	v_mov_b32_e32 v10, v2
	v_mov_b32_e32 v11, v2
	v_mov_b32_e32 v12, v2
	v_mov_b32_e32 v13, v2
	v_mov_b32_e32 v14, v2
	v_mov_b32_e32 v15, v2
	v_mov_b32_e32 v16, v2
	v_mov_b32_e32 v17, v2
	v_mov_b32_e32 v26, v2
	v_mov_b32_e32 v27, v2
	v_mov_b32_e32 v28, v2
	v_mov_b32_e32 v29, v2
	v_mov_b32_e32 v30, v2
	v_mov_b32_e32 v31, v2
	v_mov_b32_e32 v32, v2
	v_mov_b32_e32 v33, v2
	v_mov_b32_e32 v42, v2
	v_mov_b32_e32 v43, v2
	v_mov_b32_e32 v44, v2
	v_mov_b32_e32 v45, v2
	v_mov_b32_e32 v46, v2
	v_mov_b32_e32 v47, v2
	v_mov_b32_e32 v48, v2
	v_mov_b32_e32 v49, v2
	v_mov_b32_e32 v58, v2
	v_mov_b32_e32 v59, v2
	v_mov_b32_e32 v60, v2
	v_mov_b32_e32 v61, v2
	v_mov_b32_e32 v62, v2
	v_mov_b32_e32 v63, v2
	v_mov_b32_e32 v64, v2
	v_mov_b32_e32 v65, v2
	v_mov_b32_e32 v66, v2
	v_mov_b32_e32 v67, v2
	v_mov_b32_e32 v68, v2
	v_mov_b32_e32 v69, v2
	v_mov_b32_e32 v70, v2
	v_mov_b32_e32 v71, v2
	v_mov_b32_e32 v72, v2
	v_mov_b32_e32 v73, v2
	v_mov_b32_e32 v82, v2
	v_mov_b32_e32 v83, v2
	v_mov_b32_e32 v84, v2
	v_mov_b32_e32 v85, v2
	v_mov_b32_e32 v86, v2
	v_mov_b32_e32 v87, v2
	v_mov_b32_e32 v88, v2
	v_mov_b32_e32 v89, v2
	v_mov_b32_e32 v98, v2
	v_mov_b32_e32 v99, v2
	v_mov_b32_e32 v100, v2
	v_mov_b32_e32 v101, v2
	v_mov_b32_e32 v102, v2
	v_mov_b32_e32 v103, v2
	v_mov_b32_e32 v104, v2
	v_mov_b32_e32 v105, v2
	v_mov_b32_e32 v114, v2
	v_mov_b32_e32 v115, v2
	v_mov_b32_e32 v116, v2
	v_mov_b32_e32 v117, v2
	v_mov_b32_e32 v118, v2
	v_mov_b32_e32 v119, v2
	v_mov_b32_e32 v120, v2
	v_mov_b32_e32 v121, v2
	v_mov_b32_e32 v74, v2
	v_mov_b32_e32 v75, v2
	v_mov_b32_e32 v76, v2
	v_mov_b32_e32 v77, v2
	v_mov_b32_e32 v78, v2
	v_mov_b32_e32 v79, v2
	v_mov_b32_e32 v80, v2
	v_mov_b32_e32 v81, v2
	v_mov_b32_e32 v90, v2
	v_mov_b32_e32 v91, v2
	v_mov_b32_e32 v92, v2
	v_mov_b32_e32 v93, v2
	v_mov_b32_e32 v94, v2
	v_mov_b32_e32 v95, v2
	v_mov_b32_e32 v96, v2
	v_mov_b32_e32 v97, v2
	v_mov_b32_e32 v106, v2
	v_mov_b32_e32 v107, v2
	v_mov_b32_e32 v108, v2
	v_mov_b32_e32 v109, v2
	v_mov_b32_e32 v110, v2
	v_mov_b32_e32 v111, v2
	v_mov_b32_e32 v112, v2
	v_mov_b32_e32 v113, v2
	v_mov_b32_e32 v122, v2
	v_mov_b32_e32 v123, v2
	v_mov_b32_e32 v124, v2
	v_mov_b32_e32 v125, v2
	v_mov_b32_e32 v126, v2
	v_mov_b32_e32 v127, v2
	v_mov_b32_e32 v128, v2
	v_mov_b32_e32 v129, v2
	v_readfirstlane_b32 s100, v0
	s_cmp_lt_u32 s100, 0x100
	s_cbranch_scc1 .Lprio_skip_1328
	s_setprio 1
.Lprio_skip_1328:
.LBB0_1328:
	s_add_u32 s24, s22, 0x100
	s_addc_u32 s25, s23, 0
	s_add_i32 s57, 0, 0x10000
	s_cmpk_eq_i32 s56, 0xa8
	s_cselect_b32 s29, s3, s25
	s_cselect_b32 s28, s2, s24
	v_add_u32_e32 v146, s57, v149
	s_cselect_b32 s27, s17, s55
	s_cselect_b32 s26, s16, s54
	s_add_i32 s58, 0, 0x14000
	ds_read_b128 v[142:145], v146
	ds_read_b128 v[152:155], v146 offset:1024
	ds_read_b128 v[156:159], v146 offset:2048
	ds_read_b128 v[160:163], v146 offset:3072
	v_add_u32_e32 v146, s58, v149
	ds_read_b128 v[164:167], v146
	ds_read_b128 v[168:171], v146 offset:1024
	ds_read_b128 v[172:175], v146 offset:2048
	ds_read_b128 v[176:179], v146 offset:3072
	v_lshl_add_u64 v[146:147], s[22:23], 0, v[138:139]
	s_add_i32 m0, s41, 0xc000
	ds_read_b128 v[180:183], v151
	ds_read_b128 v[184:187], v151 offset:1024
	ds_read_b128 v[188:191], v151 offset:2048
	ds_read_b128 v[192:195], v151 offset:3072
	ds_read_b128 v[196:199], v151 offset:4096
	ds_read_b128 v[200:203], v151 offset:5120
	ds_read_b128 v[204:207], v151 offset:6144
	ds_read_b128 v[208:211], v151 offset:7168
	global_load_lds_dwordx4 v[146:147], off
	v_lshl_add_u64 v[146:147], s[22:23], 0, v[140:141]
	s_add_i32 m0, s41, 0xe000
	s_nop 0
	global_load_lds_dwordx4 v[146:147], off
	s_waitcnt vmcnt(8)
	s_waitcnt lgkmcnt(0)
	s_barrier
	s_waitcnt lgkmcnt(0)
	v_mfma_f32_16x16x32_bf16 v[126:129], v[142:145], v[180:183], v[126:129]
	v_mfma_f32_16x16x32_bf16 v[122:125], v[156:159], v[180:183], v[122:125]
	v_mfma_f32_16x16x32_bf16 v[110:113], v[142:145], v[188:191], v[110:113]
	v_mfma_f32_16x16x32_bf16 v[106:109], v[156:159], v[188:191], v[106:109]
	v_mfma_f32_16x16x32_bf16 v[94:97], v[142:145], v[196:199], v[94:97]
	v_mfma_f32_16x16x32_bf16 v[90:93], v[156:159], v[196:199], v[90:93]
	v_mfma_f32_16x16x32_bf16 v[78:81], v[142:145], v[204:207], v[78:81]
	v_mfma_f32_16x16x32_bf16 v[74:77], v[156:159], v[204:207], v[74:77]
	v_mfma_f32_16x16x32_bf16 v[126:129], v[152:155], v[184:187], v[126:129]
	v_mfma_f32_16x16x32_bf16 v[122:125], v[160:163], v[184:187], v[122:125]
	v_mfma_f32_16x16x32_bf16 v[110:113], v[152:155], v[192:195], v[110:113]
	v_mfma_f32_16x16x32_bf16 v[106:109], v[160:163], v[192:195], v[106:109]
	v_mfma_f32_16x16x32_bf16 v[94:97], v[152:155], v[200:203], v[94:97]
	v_mfma_f32_16x16x32_bf16 v[90:93], v[160:163], v[200:203], v[90:93]
	v_mfma_f32_16x16x32_bf16 v[78:81], v[152:155], v[208:211], v[78:81]
	v_mfma_f32_16x16x32_bf16 v[74:77], v[160:163], v[208:211], v[74:77]
	v_mfma_f32_16x16x32_bf16 v[118:121], v[164:167], v[180:183], v[118:121]
	v_mfma_f32_16x16x32_bf16 v[114:117], v[172:175], v[180:183], v[114:117]
	v_mfma_f32_16x16x32_bf16 v[102:105], v[164:167], v[188:191], v[102:105]
	v_mfma_f32_16x16x32_bf16 v[98:101], v[172:175], v[188:191], v[98:101]
	v_mfma_f32_16x16x32_bf16 v[86:89], v[164:167], v[196:199], v[86:89]
	v_mfma_f32_16x16x32_bf16 v[82:85], v[172:175], v[196:199], v[82:85]
	v_mfma_f32_16x16x32_bf16 v[70:73], v[164:167], v[204:207], v[70:73]
	v_mfma_f32_16x16x32_bf16 v[66:69], v[172:175], v[204:207], v[66:69]
	v_mfma_f32_16x16x32_bf16 v[118:121], v[168:171], v[184:187], v[118:121]
	v_mfma_f32_16x16x32_bf16 v[114:117], v[176:179], v[184:187], v[114:117]
	v_mfma_f32_16x16x32_bf16 v[102:105], v[168:171], v[192:195], v[102:105]
	v_mfma_f32_16x16x32_bf16 v[98:101], v[176:179], v[192:195], v[98:101]
	v_mfma_f32_16x16x32_bf16 v[86:89], v[168:171], v[200:203], v[86:89]
	v_mfma_f32_16x16x32_bf16 v[82:85], v[176:179], v[200:203], v[82:85]
	v_mfma_f32_16x16x32_bf16 v[70:73], v[168:171], v[208:211], v[70:73]
	v_mfma_f32_16x16x32_bf16 v[66:69], v[176:179], v[208:211], v[66:69]
	s_barrier
	s_add_i32 s22, s57, s40
	v_lshl_add_u64 v[146:147], s[26:27], 0, v[130:131]
	s_mov_b32 m0, s22
	ds_read_b128 v[180:183], v151 offset:16384
	ds_read_b128 v[184:187], v151 offset:17408
	ds_read_b128 v[188:191], v151 offset:18432
	ds_read_b128 v[192:195], v151 offset:19456
	ds_read_b128 v[196:199], v151 offset:20480
	ds_read_b128 v[200:203], v151 offset:21504
	ds_read_b128 v[204:207], v151 offset:22528
	ds_read_b128 v[208:211], v151 offset:23552
	global_load_lds_dwordx4 v[146:147], off
	s_add_i32 m0, s22, 0x2000
	s_add_u32 s22, s26, 0x2b0000
	v_lshl_add_u64 v[212:213], s[26:27], 0, v[132:133]
	s_addc_u32 s23, s27, 0
	s_add_i32 s57, s58, s40
	global_load_lds_dwordx4 v[212:213], off
	v_lshl_add_u64 v[216:217], s[22:23], 0, v[130:131]
	s_mov_b32 m0, s57
	v_lshl_add_u64 v[218:219], s[28:29], 0, v[134:135]
	global_load_lds_dwordx4 v[216:217], off
	v_lshl_add_u64 v[216:217], s[22:23], 0, v[132:133]
	s_add_i32 m0, s57, 0x2000
	s_nop 0
	global_load_lds_dwordx4 v[216:217], off
	v_lshl_add_u64 v[216:217], s[28:29], 0, v[136:137]
	s_mov_b32 m0, s41
	s_nop 0
	global_load_lds_dwordx4 v[216:217], off
	s_mov_b32 m0, s44
	s_nop 0
	global_load_lds_dwordx4 v[218:219], off
	s_waitcnt vmcnt(8)
	s_waitcnt lgkmcnt(0)
	s_barrier
	s_waitcnt lgkmcnt(0)
	v_mfma_f32_16x16x32_bf16 v[62:65], v[142:145], v[180:183], v[62:65]
	v_mfma_f32_16x16x32_bf16 v[58:61], v[156:159], v[180:183], v[58:61]
	v_mfma_f32_16x16x32_bf16 v[46:49], v[142:145], v[188:191], v[46:49]
	v_mfma_f32_16x16x32_bf16 v[42:45], v[156:159], v[188:191], v[42:45]
	v_mfma_f32_16x16x32_bf16 v[30:33], v[142:145], v[196:199], v[30:33]
	v_mfma_f32_16x16x32_bf16 v[26:29], v[156:159], v[196:199], v[26:29]
	v_mfma_f32_16x16x32_bf16 v[14:17], v[142:145], v[204:207], v[14:17]
	v_mfma_f32_16x16x32_bf16 v[10:13], v[156:159], v[204:207], v[10:13]
	v_mfma_f32_16x16x32_bf16 v[62:65], v[152:155], v[184:187], v[62:65]
	v_mfma_f32_16x16x32_bf16 v[58:61], v[160:163], v[184:187], v[58:61]
	v_mfma_f32_16x16x32_bf16 v[46:49], v[152:155], v[192:195], v[46:49]
	v_mfma_f32_16x16x32_bf16 v[42:45], v[160:163], v[192:195], v[42:45]
	v_mfma_f32_16x16x32_bf16 v[30:33], v[152:155], v[200:203], v[30:33]
	v_mfma_f32_16x16x32_bf16 v[26:29], v[160:163], v[200:203], v[26:29]
	v_mfma_f32_16x16x32_bf16 v[14:17], v[152:155], v[208:211], v[14:17]
	v_mfma_f32_16x16x32_bf16 v[10:13], v[160:163], v[208:211], v[10:13]
	v_mfma_f32_16x16x32_bf16 v[54:57], v[164:167], v[180:183], v[54:57]
	v_mfma_f32_16x16x32_bf16 v[50:53], v[172:175], v[180:183], v[50:53]
	v_mfma_f32_16x16x32_bf16 v[38:41], v[164:167], v[188:191], v[38:41]
	v_mfma_f32_16x16x32_bf16 v[34:37], v[172:175], v[188:191], v[34:37]
	v_mfma_f32_16x16x32_bf16 v[22:25], v[164:167], v[196:199], v[22:25]
	v_mfma_f32_16x16x32_bf16 v[18:21], v[172:175], v[196:199], v[18:21]
	v_mfma_f32_16x16x32_bf16 v[6:9], v[164:167], v[204:207], v[6:9]
	v_mfma_f32_16x16x32_bf16 v[2:5], v[172:175], v[204:207], v[2:5]
	v_mfma_f32_16x16x32_bf16 v[54:57], v[168:171], v[184:187], v[54:57]
	v_mfma_f32_16x16x32_bf16 v[50:53], v[176:179], v[184:187], v[50:53]
	v_mfma_f32_16x16x32_bf16 v[38:41], v[168:171], v[192:195], v[38:41]
	v_mfma_f32_16x16x32_bf16 v[34:37], v[176:179], v[192:195], v[34:37]
	v_mfma_f32_16x16x32_bf16 v[22:25], v[168:171], v[200:203], v[22:25]
	v_mfma_f32_16x16x32_bf16 v[18:21], v[176:179], v[200:203], v[18:21]
	v_mfma_f32_16x16x32_bf16 v[6:9], v[168:171], v[208:211], v[6:9]
	v_mfma_f32_16x16x32_bf16 v[2:5], v[176:179], v[208:211], v[2:5]
	s_barrier
	s_add_i32 s57, 0, 0x18000
	s_add_i32 s58, 0, 0x1c000
	v_add_u32_e32 v160, s57, v149
	v_add_u32_e32 v176, s58, v149
	ds_read_b128 v[142:145], v160
	ds_read_b128 v[152:155], v160 offset:1024
	ds_read_b128 v[156:159], v160 offset:2048
	ds_read_b128 v[160:163], v160 offset:3072
	ds_read_b128 v[164:167], v176
	ds_read_b128 v[168:171], v176 offset:1024
	ds_read_b128 v[172:175], v176 offset:2048
	ds_read_b128 v[176:179], v176 offset:3072
	s_add_u32 s22, s28, 0x2b0000
	s_addc_u32 s23, s29, 0
	s_mov_b32 m0, s45
	v_lshl_add_u64 v[220:221], s[22:23], 0, v[136:137]
	ds_read_b128 v[180:183], v151 offset:32768
	ds_read_b128 v[184:187], v151 offset:33792
	ds_read_b128 v[188:191], v151 offset:34816
	ds_read_b128 v[192:195], v151 offset:35840
	ds_read_b128 v[196:199], v151 offset:36864
	ds_read_b128 v[200:203], v151 offset:37888
	ds_read_b128 v[204:207], v151 offset:38912
	ds_read_b128 v[208:211], v151 offset:39936
	global_load_lds_dwordx4 v[220:221], off
	v_lshl_add_u64 v[220:221], s[22:23], 0, v[134:135]
	s_mov_b32 m0, s46
	s_nop 0
	global_load_lds_dwordx4 v[220:221], off
	s_waitcnt vmcnt(8)
	s_waitcnt lgkmcnt(0)
	s_barrier
	s_waitcnt lgkmcnt(0)
	v_mfma_f32_16x16x32_bf16 v[126:129], v[142:145], v[180:183], v[126:129]
	v_mfma_f32_16x16x32_bf16 v[122:125], v[156:159], v[180:183], v[122:125]
	v_mfma_f32_16x16x32_bf16 v[110:113], v[142:145], v[188:191], v[110:113]
	v_mfma_f32_16x16x32_bf16 v[106:109], v[156:159], v[188:191], v[106:109]
	v_mfma_f32_16x16x32_bf16 v[94:97], v[142:145], v[196:199], v[94:97]
	v_mfma_f32_16x16x32_bf16 v[90:93], v[156:159], v[196:199], v[90:93]
	v_mfma_f32_16x16x32_bf16 v[78:81], v[142:145], v[204:207], v[78:81]
	v_mfma_f32_16x16x32_bf16 v[74:77], v[156:159], v[204:207], v[74:77]
	v_mfma_f32_16x16x32_bf16 v[126:129], v[152:155], v[184:187], v[126:129]
	v_mfma_f32_16x16x32_bf16 v[122:125], v[160:163], v[184:187], v[122:125]
	v_mfma_f32_16x16x32_bf16 v[110:113], v[152:155], v[192:195], v[110:113]
	v_mfma_f32_16x16x32_bf16 v[106:109], v[160:163], v[192:195], v[106:109]
	v_mfma_f32_16x16x32_bf16 v[94:97], v[152:155], v[200:203], v[94:97]
	v_mfma_f32_16x16x32_bf16 v[90:93], v[160:163], v[200:203], v[90:93]
	v_mfma_f32_16x16x32_bf16 v[78:81], v[152:155], v[208:211], v[78:81]
	v_mfma_f32_16x16x32_bf16 v[74:77], v[160:163], v[208:211], v[74:77]
	v_mfma_f32_16x16x32_bf16 v[118:121], v[164:167], v[180:183], v[118:121]
	v_mfma_f32_16x16x32_bf16 v[114:117], v[172:175], v[180:183], v[114:117]
	v_mfma_f32_16x16x32_bf16 v[102:105], v[164:167], v[188:191], v[102:105]
	v_mfma_f32_16x16x32_bf16 v[98:101], v[172:175], v[188:191], v[98:101]
	v_mfma_f32_16x16x32_bf16 v[86:89], v[164:167], v[196:199], v[86:89]
	v_mfma_f32_16x16x32_bf16 v[82:85], v[172:175], v[196:199], v[82:85]
	v_mfma_f32_16x16x32_bf16 v[70:73], v[164:167], v[204:207], v[70:73]
	v_mfma_f32_16x16x32_bf16 v[66:69], v[172:175], v[204:207], v[66:69]
	v_mfma_f32_16x16x32_bf16 v[118:121], v[168:171], v[184:187], v[118:121]
	v_mfma_f32_16x16x32_bf16 v[114:117], v[176:179], v[184:187], v[114:117]
	v_mfma_f32_16x16x32_bf16 v[102:105], v[168:171], v[192:195], v[102:105]
	v_mfma_f32_16x16x32_bf16 v[98:101], v[176:179], v[192:195], v[98:101]
	v_mfma_f32_16x16x32_bf16 v[86:89], v[168:171], v[200:203], v[86:89]
	v_mfma_f32_16x16x32_bf16 v[82:85], v[176:179], v[200:203], v[82:85]
	v_mfma_f32_16x16x32_bf16 v[70:73], v[168:171], v[208:211], v[70:73]
	v_mfma_f32_16x16x32_bf16 v[66:69], v[176:179], v[208:211], v[66:69]
	s_barrier
	s_add_i32 s22, s57, s40
	v_lshl_add_u64 v[146:147], v[146:147], 0, s[18:19]
	s_mov_b32 m0, s22
	ds_read_b128 v[180:183], v151 offset:49152
	ds_read_b128 v[184:187], v151 offset:50176
	ds_read_b128 v[188:191], v151 offset:51200
	ds_read_b128 v[192:195], v151 offset:52224
	ds_read_b128 v[196:199], v151 offset:53248
	ds_read_b128 v[200:203], v151 offset:54272
	ds_read_b128 v[204:207], v151 offset:55296
	ds_read_b128 v[208:211], v151 offset:56320
	global_load_lds_dwordx4 v[146:147], off
	s_add_i32 m0, s22, 0x2000
	s_add_u32 s22, s26, 0x2b0080
	v_lshl_add_u64 v[146:147], v[212:213], 0, s[18:19]
	s_addc_u32 s23, s27, 0
	s_add_i32 s26, s58, s40
	global_load_lds_dwordx4 v[146:147], off
	v_lshl_add_u64 v[146:147], s[22:23], 0, v[130:131]
	s_mov_b32 m0, s26
	s_nop 0
	global_load_lds_dwordx4 v[146:147], off
	v_lshl_add_u64 v[146:147], s[22:23], 0, v[132:133]
	s_add_i32 m0, s26, 0x2000
	s_nop 0
	global_load_lds_dwordx4 v[146:147], off
	v_lshl_add_u64 v[146:147], v[216:217], 0, s[18:19]
	s_mov_b32 m0, s47
	s_nop 0
	global_load_lds_dwordx4 v[146:147], off
	v_lshl_add_u64 v[146:147], v[218:219], 0, s[18:19]
	s_mov_b32 m0, s48
	s_nop 0
	global_load_lds_dwordx4 v[146:147], off
	s_waitcnt vmcnt(8)
	s_waitcnt lgkmcnt(0)
	s_barrier
	s_waitcnt lgkmcnt(0)
	v_mfma_f32_16x16x32_bf16 v[62:65], v[142:145], v[180:183], v[62:65]
	v_mfma_f32_16x16x32_bf16 v[58:61], v[156:159], v[180:183], v[58:61]
	v_mfma_f32_16x16x32_bf16 v[46:49], v[142:145], v[188:191], v[46:49]
	v_mfma_f32_16x16x32_bf16 v[42:45], v[156:159], v[188:191], v[42:45]
	v_mfma_f32_16x16x32_bf16 v[30:33], v[142:145], v[196:199], v[30:33]
	v_mfma_f32_16x16x32_bf16 v[26:29], v[156:159], v[196:199], v[26:29]
	v_mfma_f32_16x16x32_bf16 v[14:17], v[142:145], v[204:207], v[14:17]
	v_mfma_f32_16x16x32_bf16 v[10:13], v[156:159], v[204:207], v[10:13]
	v_mfma_f32_16x16x32_bf16 v[62:65], v[152:155], v[184:187], v[62:65]
	v_mfma_f32_16x16x32_bf16 v[58:61], v[160:163], v[184:187], v[58:61]
	v_mfma_f32_16x16x32_bf16 v[46:49], v[152:155], v[192:195], v[46:49]
	v_mfma_f32_16x16x32_bf16 v[42:45], v[160:163], v[192:195], v[42:45]
	v_mfma_f32_16x16x32_bf16 v[30:33], v[152:155], v[200:203], v[30:33]
	v_mfma_f32_16x16x32_bf16 v[26:29], v[160:163], v[200:203], v[26:29]
	v_mfma_f32_16x16x32_bf16 v[14:17], v[152:155], v[208:211], v[14:17]
	v_mfma_f32_16x16x32_bf16 v[10:13], v[160:163], v[208:211], v[10:13]
	v_mfma_f32_16x16x32_bf16 v[54:57], v[164:167], v[180:183], v[54:57]
	v_mfma_f32_16x16x32_bf16 v[50:53], v[172:175], v[180:183], v[50:53]
	v_mfma_f32_16x16x32_bf16 v[38:41], v[164:167], v[188:191], v[38:41]
	v_mfma_f32_16x16x32_bf16 v[34:37], v[172:175], v[188:191], v[34:37]
	v_mfma_f32_16x16x32_bf16 v[22:25], v[164:167], v[196:199], v[22:25]
	v_mfma_f32_16x16x32_bf16 v[18:21], v[172:175], v[196:199], v[18:21]
	v_mfma_f32_16x16x32_bf16 v[6:9], v[164:167], v[204:207], v[6:9]
	v_mfma_f32_16x16x32_bf16 v[2:5], v[172:175], v[204:207], v[2:5]
	v_mfma_f32_16x16x32_bf16 v[54:57], v[168:171], v[184:187], v[54:57]
	v_mfma_f32_16x16x32_bf16 v[50:53], v[176:179], v[184:187], v[50:53]
	v_mfma_f32_16x16x32_bf16 v[38:41], v[168:171], v[192:195], v[38:41]
	v_mfma_f32_16x16x32_bf16 v[34:37], v[176:179], v[192:195], v[34:37]
	v_mfma_f32_16x16x32_bf16 v[22:25], v[168:171], v[200:203], v[22:25]
	v_mfma_f32_16x16x32_bf16 v[18:21], v[176:179], v[200:203], v[18:21]
	v_mfma_f32_16x16x32_bf16 v[6:9], v[168:171], v[208:211], v[6:9]
	v_mfma_f32_16x16x32_bf16 v[2:5], v[176:179], v[208:211], v[2:5]
	s_barrier
	s_add_i32 s56, s56, 2
	s_add_u32 s54, s54, 0x100
	s_addc_u32 s55, s55, 0
	s_cmpk_gt_u32 s56, 0xa9
	s_mov_b64 s[22:23], s[24:25]
	s_cbranch_scc0 .LBB0_1328
	s_setprio 0
	s_and_b64 vcc, exec, s[12:13]
	s_cbranch_vccz .LBB0_1331
	s_barrier

.LBB0_1353:
	s_add_u32 s57, s24, 0x100
	v_mov_b32_e32 v2, 0
	s_addc_u32 s58, s25, 0
	s_mov_b32 s59, -2
	v_mov_b32_e32 v3, v2
	v_mov_b32_e32 v4, v2
	v_mov_b32_e32 v5, v2
	v_mov_b32_e32 v6, v2
	v_mov_b32_e32 v7, v2
	v_mov_b32_e32 v8, v2
	v_mov_b32_e32 v9, v2
	v_mov_b32_e32 v18, v2
	v_mov_b32_e32 v19, v2
	v_mov_b32_e32 v20, v2
	v_mov_b32_e32 v21, v2
	v_mov_b32_e32 v22, v2
	v_mov_b32_e32 v23, v2
	v_mov_b32_e32 v24, v2
	v_mov_b32_e32 v25, v2
	s_waitcnt vmcnt(0)
	v_mov_b32_e32 v34, v2
	v_mov_b32_e32 v35, v2
	v_mov_b32_e32 v36, v2
	v_mov_b32_e32 v37, v2
	v_mov_b32_e32 v38, v2
	v_mov_b32_e32 v39, v2
	v_mov_b32_e32 v40, v2
	v_mov_b32_e32 v41, v2
	v_mov_b32_e32 v50, v2
	v_mov_b32_e32 v51, v2
	v_mov_b32_e32 v52, v2
	v_mov_b32_e32 v53, v2
	v_mov_b32_e32 v54, v2
	v_mov_b32_e32 v55, v2
	v_mov_b32_e32 v56, v2
	v_mov_b32_e32 v57, v2
	v_mov_b32_e32 v10, v2
	v_mov_b32_e32 v11, v2
	v_mov_b32_e32 v12, v2
	v_mov_b32_e32 v13, v2
	v_mov_b32_e32 v14, v2
	v_mov_b32_e32 v15, v2
	v_mov_b32_e32 v16, v2
	v_mov_b32_e32 v17, v2
	v_mov_b32_e32 v26, v2
	v_mov_b32_e32 v27, v2
	v_mov_b32_e32 v28, v2
	v_mov_b32_e32 v29, v2
	v_mov_b32_e32 v30, v2
	v_mov_b32_e32 v31, v2
	v_mov_b32_e32 v32, v2
	v_mov_b32_e32 v33, v2
	v_mov_b32_e32 v42, v2
	v_mov_b32_e32 v43, v2
	v_mov_b32_e32 v44, v2
	v_mov_b32_e32 v45, v2
	v_mov_b32_e32 v46, v2
	v_mov_b32_e32 v47, v2
	v_mov_b32_e32 v48, v2
	v_mov_b32_e32 v49, v2
	v_mov_b32_e32 v58, v2
	v_mov_b32_e32 v59, v2
	v_mov_b32_e32 v60, v2
	v_mov_b32_e32 v61, v2
	v_mov_b32_e32 v62, v2
	v_mov_b32_e32 v63, v2
	v_mov_b32_e32 v64, v2
	v_mov_b32_e32 v65, v2
	v_mov_b32_e32 v66, v2
	v_mov_b32_e32 v67, v2
	v_mov_b32_e32 v68, v2
	v_mov_b32_e32 v69, v2
	v_mov_b32_e32 v70, v2
	v_mov_b32_e32 v71, v2
	v_mov_b32_e32 v72, v2
	v_mov_b32_e32 v73, v2
	v_mov_b32_e32 v82, v2
	v_mov_b32_e32 v83, v2
	v_mov_b32_e32 v84, v2
	v_mov_b32_e32 v85, v2
	v_mov_b32_e32 v86, v2
	v_mov_b32_e32 v87, v2
	v_mov_b32_e32 v88, v2
	v_mov_b32_e32 v89, v2
	v_mov_b32_e32 v98, v2
	v_mov_b32_e32 v99, v2
	v_mov_b32_e32 v100, v2
	v_mov_b32_e32 v101, v2
	v_mov_b32_e32 v102, v2
	v_mov_b32_e32 v103, v2
	v_mov_b32_e32 v104, v2
	v_mov_b32_e32 v105, v2
	v_mov_b32_e32 v114, v2
	v_mov_b32_e32 v115, v2
	v_mov_b32_e32 v116, v2
	v_mov_b32_e32 v117, v2
	v_mov_b32_e32 v118, v2
	v_mov_b32_e32 v119, v2
	v_mov_b32_e32 v120, v2
	v_mov_b32_e32 v121, v2
	v_mov_b32_e32 v74, v2
	v_mov_b32_e32 v75, v2
	v_mov_b32_e32 v76, v2
	v_mov_b32_e32 v77, v2
	v_mov_b32_e32 v78, v2
	v_mov_b32_e32 v79, v2
	v_mov_b32_e32 v80, v2
	v_mov_b32_e32 v81, v2
	v_mov_b32_e32 v90, v2
	v_mov_b32_e32 v91, v2
	v_mov_b32_e32 v92, v2
	v_mov_b32_e32 v93, v2
	v_mov_b32_e32 v94, v2
	v_mov_b32_e32 v95, v2
	v_mov_b32_e32 v96, v2
	v_mov_b32_e32 v97, v2
	v_mov_b32_e32 v106, v2
	v_mov_b32_e32 v107, v2
	v_mov_b32_e32 v108, v2
	v_mov_b32_e32 v109, v2
	v_mov_b32_e32 v110, v2
	v_mov_b32_e32 v111, v2
	v_mov_b32_e32 v112, v2
	v_mov_b32_e32 v113, v2
	v_mov_b32_e32 v122, v2
	v_mov_b32_e32 v123, v2
	v_mov_b32_e32 v124, v2
	v_mov_b32_e32 v125, v2
	v_mov_b32_e32 v126, v2
	v_mov_b32_e32 v127, v2
	v_mov_b32_e32 v128, v2
	v_mov_b32_e32 v129, v2
	v_readfirstlane_b32 s100, v0
	s_cmp_lt_u32 s100, 0x100
	s_cbranch_scc1 .Lprio_skip_1354
	s_setprio 1
.Lprio_skip_1354:
.LBB0_1354:
	s_add_u32 s24, s22, 0x100
	s_addc_u32 s25, s23, 0
	s_add_i32 s60, 0, 0x10000
	s_cmpk_eq_i32 s59, 0xa8
	s_cselect_b32 s29, s3, s25
	s_cselect_b32 s28, s2, s24
	v_add_u32_e32 v149, s60, v194
	s_cselect_b32 s27, s13, s58
	s_cselect_b32 s26, s12, s57
	s_add_i32 s61, 0, 0x14000
	ds_read_b128 v[132:135], v149
	ds_read_b128 v[150:153], v149 offset:1024
	ds_read_b128 v[154:157], v149 offset:2048
	ds_read_b128 v[158:161], v149 offset:3072
	v_add_u32_e32 v149, s61, v194
	ds_read_b128 v[162:165], v149
	ds_read_b128 v[166:169], v149 offset:1024
	ds_read_b128 v[170:173], v149 offset:2048
	ds_read_b128 v[174:177], v149 offset:3072
	v_lshl_add_u64 v[190:191], s[22:23], 0, v[144:145]
	s_add_i32 m0, s48, 0xc000
	ds_read_b128 v[178:181], v196
	ds_read_b128 v[182:185], v196 offset:1024
	ds_read_b128 v[186:189], v196 offset:2048
	ds_read_b128 v[198:201], v196 offset:3072
	ds_read_b128 v[202:205], v196 offset:4096
	ds_read_b128 v[206:209], v196 offset:5120
	ds_read_b128 v[210:213], v196 offset:6144
	ds_read_b128 v[216:219], v196 offset:7168
	global_load_lds_dwordx4 v[190:191], off
	v_lshl_add_u64 v[190:191], s[22:23], 0, v[146:147]
	s_add_i32 m0, s48, 0xe000
	s_nop 0
	global_load_lds_dwordx4 v[190:191], off
	s_waitcnt vmcnt(8)
	s_waitcnt lgkmcnt(0)
	s_barrier
	s_waitcnt lgkmcnt(0)
	v_mfma_f32_16x16x32_bf16 v[126:129], v[132:135], v[178:181], v[126:129]
	v_mfma_f32_16x16x32_bf16 v[122:125], v[154:157], v[178:181], v[122:125]
	v_mfma_f32_16x16x32_bf16 v[110:113], v[132:135], v[186:189], v[110:113]
	v_mfma_f32_16x16x32_bf16 v[106:109], v[154:157], v[186:189], v[106:109]
	v_mfma_f32_16x16x32_bf16 v[94:97], v[132:135], v[202:205], v[94:97]
	v_mfma_f32_16x16x32_bf16 v[90:93], v[154:157], v[202:205], v[90:93]
	v_mfma_f32_16x16x32_bf16 v[78:81], v[132:135], v[210:213], v[78:81]
	v_mfma_f32_16x16x32_bf16 v[74:77], v[154:157], v[210:213], v[74:77]
	v_mfma_f32_16x16x32_bf16 v[126:129], v[150:153], v[182:185], v[126:129]
	v_mfma_f32_16x16x32_bf16 v[122:125], v[158:161], v[182:185], v[122:125]
	v_mfma_f32_16x16x32_bf16 v[110:113], v[150:153], v[198:201], v[110:113]
	v_mfma_f32_16x16x32_bf16 v[106:109], v[158:161], v[198:201], v[106:109]
	v_mfma_f32_16x16x32_bf16 v[94:97], v[150:153], v[206:209], v[94:97]
	v_mfma_f32_16x16x32_bf16 v[90:93], v[158:161], v[206:209], v[90:93]
	v_mfma_f32_16x16x32_bf16 v[78:81], v[150:153], v[216:219], v[78:81]
	v_mfma_f32_16x16x32_bf16 v[74:77], v[158:161], v[216:219], v[74:77]
	v_mfma_f32_16x16x32_bf16 v[118:121], v[162:165], v[178:181], v[118:121]
	v_mfma_f32_16x16x32_bf16 v[114:117], v[170:173], v[178:181], v[114:117]
	v_mfma_f32_16x16x32_bf16 v[102:105], v[162:165], v[186:189], v[102:105]
	v_mfma_f32_16x16x32_bf16 v[98:101], v[170:173], v[186:189], v[98:101]
	v_mfma_f32_16x16x32_bf16 v[86:89], v[162:165], v[202:205], v[86:89]
	v_mfma_f32_16x16x32_bf16 v[82:85], v[170:173], v[202:205], v[82:85]
	v_mfma_f32_16x16x32_bf16 v[70:73], v[162:165], v[210:213], v[70:73]
	v_mfma_f32_16x16x32_bf16 v[66:69], v[170:173], v[210:213], v[66:69]
	v_mfma_f32_16x16x32_bf16 v[118:121], v[166:169], v[182:185], v[118:121]
	v_mfma_f32_16x16x32_bf16 v[114:117], v[174:177], v[182:185], v[114:117]
	v_mfma_f32_16x16x32_bf16 v[102:105], v[166:169], v[198:201], v[102:105]
	v_mfma_f32_16x16x32_bf16 v[98:101], v[174:177], v[198:201], v[98:101]
	v_mfma_f32_16x16x32_bf16 v[86:89], v[166:169], v[206:209], v[86:89]
	v_mfma_f32_16x16x32_bf16 v[82:85], v[174:177], v[206:209], v[82:85]
	v_mfma_f32_16x16x32_bf16 v[70:73], v[166:169], v[216:219], v[70:73]
	v_mfma_f32_16x16x32_bf16 v[66:69], v[174:177], v[216:219], v[66:69]
	s_barrier
	s_add_i32 s22, s60, s30
	v_lshl_add_u64 v[190:191], s[26:27], 0, v[140:141]
	s_mov_b32 m0, s22
	ds_read_b128 v[178:181], v196 offset:16384
	ds_read_b128 v[182:185], v196 offset:17408
	ds_read_b128 v[186:189], v196 offset:18432
	ds_read_b128 v[198:201], v196 offset:19456
	ds_read_b128 v[202:205], v196 offset:20480
	ds_read_b128 v[206:209], v196 offset:21504
	ds_read_b128 v[210:213], v196 offset:22528
	ds_read_b128 v[216:219], v196 offset:23552
	global_load_lds_dwordx4 v[190:191], off
	s_add_i32 m0, s22, 0x2000
	s_add_u32 s22, s26, 0x2b0000
	v_lshl_add_u64 v[220:221], s[26:27], 0, v[136:137]
	s_addc_u32 s23, s27, 0
	s_add_i32 s60, s61, s30
	global_load_lds_dwordx4 v[220:221], off
	v_lshl_add_u64 v[222:223], s[22:23], 0, v[140:141]
	s_mov_b32 m0, s60
	v_lshl_add_u64 v[224:225], s[28:29], 0, v[138:139]
	global_load_lds_dwordx4 v[222:223], off
	v_lshl_add_u64 v[222:223], s[22:23], 0, v[136:137]
	s_add_i32 m0, s60, 0x2000
	s_nop 0
	global_load_lds_dwordx4 v[222:223], off
	v_lshl_add_u64 v[222:223], s[28:29], 0, v[142:143]
	s_mov_b32 m0, s48
	s_nop 0
	global_load_lds_dwordx4 v[222:223], off
	s_mov_b32 m0, s49
	s_nop 0
	global_load_lds_dwordx4 v[224:225], off
	s_waitcnt vmcnt(8)
	s_waitcnt lgkmcnt(0)
	s_barrier
	s_waitcnt lgkmcnt(0)
	v_mfma_f32_16x16x32_bf16 v[62:65], v[132:135], v[178:181], v[62:65]
	v_mfma_f32_16x16x32_bf16 v[58:61], v[154:157], v[178:181], v[58:61]
	v_mfma_f32_16x16x32_bf16 v[46:49], v[132:135], v[186:189], v[46:49]
	v_mfma_f32_16x16x32_bf16 v[42:45], v[154:157], v[186:189], v[42:45]
	v_mfma_f32_16x16x32_bf16 v[30:33], v[132:135], v[202:205], v[30:33]
	v_mfma_f32_16x16x32_bf16 v[26:29], v[154:157], v[202:205], v[26:29]
	v_mfma_f32_16x16x32_bf16 v[14:17], v[132:135], v[210:213], v[14:17]
	v_mfma_f32_16x16x32_bf16 v[10:13], v[154:157], v[210:213], v[10:13]
	v_mfma_f32_16x16x32_bf16 v[62:65], v[150:153], v[182:185], v[62:65]
	v_mfma_f32_16x16x32_bf16 v[58:61], v[158:161], v[182:185], v[58:61]
	v_mfma_f32_16x16x32_bf16 v[46:49], v[150:153], v[198:201], v[46:49]
	v_mfma_f32_16x16x32_bf16 v[42:45], v[158:161], v[198:201], v[42:45]
	v_mfma_f32_16x16x32_bf16 v[30:33], v[150:153], v[206:209], v[30:33]
	v_mfma_f32_16x16x32_bf16 v[26:29], v[158:161], v[206:209], v[26:29]
	v_mfma_f32_16x16x32_bf16 v[14:17], v[150:153], v[216:219], v[14:17]
	v_mfma_f32_16x16x32_bf16 v[10:13], v[158:161], v[216:219], v[10:13]
	v_mfma_f32_16x16x32_bf16 v[54:57], v[162:165], v[178:181], v[54:57]
	v_mfma_f32_16x16x32_bf16 v[50:53], v[170:173], v[178:181], v[50:53]
	v_mfma_f32_16x16x32_bf16 v[38:41], v[162:165], v[186:189], v[38:41]
	v_mfma_f32_16x16x32_bf16 v[34:37], v[170:173], v[186:189], v[34:37]
	v_mfma_f32_16x16x32_bf16 v[22:25], v[162:165], v[202:205], v[22:25]
	v_mfma_f32_16x16x32_bf16 v[18:21], v[170:173], v[202:205], v[18:21]
	v_mfma_f32_16x16x32_bf16 v[6:9], v[162:165], v[210:213], v[6:9]
	v_mfma_f32_16x16x32_bf16 v[2:5], v[170:173], v[210:213], v[2:5]
	v_mfma_f32_16x16x32_bf16 v[54:57], v[166:169], v[182:185], v[54:57]
	v_mfma_f32_16x16x32_bf16 v[50:53], v[174:177], v[182:185], v[50:53]
	v_mfma_f32_16x16x32_bf16 v[38:41], v[166:169], v[198:201], v[38:41]
	v_mfma_f32_16x16x32_bf16 v[34:37], v[174:177], v[198:201], v[34:37]
	v_mfma_f32_16x16x32_bf16 v[22:25], v[166:169], v[206:209], v[22:25]
	v_mfma_f32_16x16x32_bf16 v[18:21], v[174:177], v[206:209], v[18:21]
	v_mfma_f32_16x16x32_bf16 v[6:9], v[166:169], v[216:219], v[6:9]
	v_mfma_f32_16x16x32_bf16 v[2:5], v[174:177], v[216:219], v[2:5]
	s_barrier
	s_add_i32 s60, 0, 0x18000
	v_add_u32_e32 v149, s60, v194
	s_add_i32 s61, 0, 0x1c000
	ds_read_b128 v[132:135], v149
	ds_read_b128 v[150:153], v149 offset:1024
	ds_read_b128 v[154:157], v149 offset:2048
	ds_read_b128 v[158:161], v149 offset:3072
	v_add_u32_e32 v149, s61, v194
	ds_read_b128 v[162:165], v149
	ds_read_b128 v[166:169], v149 offset:1024
	ds_read_b128 v[170:173], v149 offset:2048
	ds_read_b128 v[174:177], v149 offset:3072
	s_add_u32 s22, s28, 0x2b0000
	s_addc_u32 s23, s29, 0
	s_mov_b32 m0, s50
	v_lshl_add_u64 v[226:227], s[22:23], 0, v[142:143]
	ds_read_b128 v[178:181], v196 offset:32768
	ds_read_b128 v[182:185], v196 offset:33792
	ds_read_b128 v[186:189], v196 offset:34816
	ds_read_b128 v[198:201], v196 offset:35840
	ds_read_b128 v[202:205], v196 offset:36864
	ds_read_b128 v[206:209], v196 offset:37888
	ds_read_b128 v[210:213], v196 offset:38912
	ds_read_b128 v[216:219], v196 offset:39936
	global_load_lds_dwordx4 v[226:227], off
	v_lshl_add_u64 v[226:227], s[22:23], 0, v[138:139]
	s_mov_b32 m0, s51
	s_nop 0
	global_load_lds_dwordx4 v[226:227], off
	s_waitcnt vmcnt(8)
	s_waitcnt lgkmcnt(0)
	s_barrier
	s_waitcnt lgkmcnt(0)
	v_mfma_f32_16x16x32_bf16 v[126:129], v[132:135], v[178:181], v[126:129]
	v_mfma_f32_16x16x32_bf16 v[122:125], v[154:157], v[178:181], v[122:125]
	v_mfma_f32_16x16x32_bf16 v[110:113], v[132:135], v[186:189], v[110:113]
	v_mfma_f32_16x16x32_bf16 v[106:109], v[154:157], v[186:189], v[106:109]
	v_mfma_f32_16x16x32_bf16 v[94:97], v[132:135], v[202:205], v[94:97]
	v_mfma_f32_16x16x32_bf16 v[90:93], v[154:157], v[202:205], v[90:93]
	v_mfma_f32_16x16x32_bf16 v[78:81], v[132:135], v[210:213], v[78:81]
	v_mfma_f32_16x16x32_bf16 v[74:77], v[154:157], v[210:213], v[74:77]
	v_mfma_f32_16x16x32_bf16 v[126:129], v[150:153], v[182:185], v[126:129]
	v_mfma_f32_16x16x32_bf16 v[122:125], v[158:161], v[182:185], v[122:125]
	v_mfma_f32_16x16x32_bf16 v[110:113], v[150:153], v[198:201], v[110:113]
	v_mfma_f32_16x16x32_bf16 v[106:109], v[158:161], v[198:201], v[106:109]
	v_mfma_f32_16x16x32_bf16 v[94:97], v[150:153], v[206:209], v[94:97]
	v_mfma_f32_16x16x32_bf16 v[90:93], v[158:161], v[206:209], v[90:93]
	v_mfma_f32_16x16x32_bf16 v[78:81], v[150:153], v[216:219], v[78:81]
	v_mfma_f32_16x16x32_bf16 v[74:77], v[158:161], v[216:219], v[74:77]
	v_mfma_f32_16x16x32_bf16 v[118:121], v[162:165], v[178:181], v[118:121]
	v_mfma_f32_16x16x32_bf16 v[114:117], v[170:173], v[178:181], v[114:117]
	v_mfma_f32_16x16x32_bf16 v[102:105], v[162:165], v[186:189], v[102:105]
	v_mfma_f32_16x16x32_bf16 v[98:101], v[170:173], v[186:189], v[98:101]
	v_mfma_f32_16x16x32_bf16 v[86:89], v[162:165], v[202:205], v[86:89]
	v_mfma_f32_16x16x32_bf16 v[82:85], v[170:173], v[202:205], v[82:85]
	v_mfma_f32_16x16x32_bf16 v[70:73], v[162:165], v[210:213], v[70:73]
	v_mfma_f32_16x16x32_bf16 v[66:69], v[170:173], v[210:213], v[66:69]
	v_mfma_f32_16x16x32_bf16 v[118:121], v[166:169], v[182:185], v[118:121]
	v_mfma_f32_16x16x32_bf16 v[114:117], v[174:177], v[182:185], v[114:117]
	v_mfma_f32_16x16x32_bf16 v[102:105], v[166:169], v[198:201], v[102:105]
	v_mfma_f32_16x16x32_bf16 v[98:101], v[174:177], v[198:201], v[98:101]
	v_mfma_f32_16x16x32_bf16 v[86:89], v[166:169], v[206:209], v[86:89]
	v_mfma_f32_16x16x32_bf16 v[82:85], v[174:177], v[206:209], v[82:85]
	v_mfma_f32_16x16x32_bf16 v[70:73], v[166:169], v[216:219], v[70:73]
	v_mfma_f32_16x16x32_bf16 v[66:69], v[174:177], v[216:219], v[66:69]
	s_barrier
	s_add_i32 s22, s60, s30
	v_lshl_add_u64 v[190:191], v[190:191], 0, s[18:19]
	s_mov_b32 m0, s22
	ds_read_b128 v[178:181], v196 offset:49152
	ds_read_b128 v[182:185], v196 offset:50176
	ds_read_b128 v[186:189], v196 offset:51200
	ds_read_b128 v[198:201], v196 offset:52224
	ds_read_b128 v[202:205], v196 offset:53248
	ds_read_b128 v[206:209], v196 offset:54272
	ds_read_b128 v[210:213], v196 offset:55296
	ds_read_b128 v[216:219], v196 offset:56320
	global_load_lds_dwordx4 v[190:191], off
	s_add_i32 m0, s22, 0x2000
	s_add_u32 s22, s26, 0x2b0080
	v_lshl_add_u64 v[190:191], v[220:221], 0, s[18:19]
	s_addc_u32 s23, s27, 0
	s_add_i32 s26, s61, s30
	global_load_lds_dwordx4 v[190:191], off
	v_lshl_add_u64 v[190:191], s[22:23], 0, v[140:141]
	s_mov_b32 m0, s26
	s_nop 0
	global_load_lds_dwordx4 v[190:191], off
	v_lshl_add_u64 v[190:191], s[22:23], 0, v[136:137]
	s_add_i32 m0, s26, 0x2000
	s_nop 0
	global_load_lds_dwordx4 v[190:191], off
	v_lshl_add_u64 v[190:191], v[222:223], 0, s[18:19]
	s_mov_b32 m0, s52
	s_nop 0
	global_load_lds_dwordx4 v[190:191], off
	v_lshl_add_u64 v[190:191], v[224:225], 0, s[18:19]
	s_mov_b32 m0, s53
	s_nop 0
	global_load_lds_dwordx4 v[190:191], off
	s_waitcnt vmcnt(8)
	s_waitcnt lgkmcnt(0)
	s_barrier
	s_waitcnt lgkmcnt(0)
	v_mfma_f32_16x16x32_bf16 v[62:65], v[132:135], v[178:181], v[62:65]
	v_mfma_f32_16x16x32_bf16 v[58:61], v[154:157], v[178:181], v[58:61]
	v_mfma_f32_16x16x32_bf16 v[46:49], v[132:135], v[186:189], v[46:49]
	v_mfma_f32_16x16x32_bf16 v[42:45], v[154:157], v[186:189], v[42:45]
	v_mfma_f32_16x16x32_bf16 v[30:33], v[132:135], v[202:205], v[30:33]
	v_mfma_f32_16x16x32_bf16 v[26:29], v[154:157], v[202:205], v[26:29]
	v_mfma_f32_16x16x32_bf16 v[14:17], v[132:135], v[210:213], v[14:17]
	v_mfma_f32_16x16x32_bf16 v[10:13], v[154:157], v[210:213], v[10:13]
	v_mfma_f32_16x16x32_bf16 v[62:65], v[150:153], v[182:185], v[62:65]
	v_mfma_f32_16x16x32_bf16 v[58:61], v[158:161], v[182:185], v[58:61]
	v_mfma_f32_16x16x32_bf16 v[46:49], v[150:153], v[198:201], v[46:49]
	v_mfma_f32_16x16x32_bf16 v[42:45], v[158:161], v[198:201], v[42:45]
	v_mfma_f32_16x16x32_bf16 v[30:33], v[150:153], v[206:209], v[30:33]
	v_mfma_f32_16x16x32_bf16 v[26:29], v[158:161], v[206:209], v[26:29]
	v_mfma_f32_16x16x32_bf16 v[14:17], v[150:153], v[216:219], v[14:17]
	v_mfma_f32_16x16x32_bf16 v[10:13], v[158:161], v[216:219], v[10:13]
	v_mfma_f32_16x16x32_bf16 v[54:57], v[162:165], v[178:181], v[54:57]
	v_mfma_f32_16x16x32_bf16 v[50:53], v[170:173], v[178:181], v[50:53]
	v_mfma_f32_16x16x32_bf16 v[38:41], v[162:165], v[186:189], v[38:41]
	v_mfma_f32_16x16x32_bf16 v[34:37], v[170:173], v[186:189], v[34:37]
	v_mfma_f32_16x16x32_bf16 v[22:25], v[162:165], v[202:205], v[22:25]
	v_mfma_f32_16x16x32_bf16 v[18:21], v[170:173], v[202:205], v[18:21]
	v_mfma_f32_16x16x32_bf16 v[6:9], v[162:165], v[210:213], v[6:9]
	v_mfma_f32_16x16x32_bf16 v[2:5], v[170:173], v[210:213], v[2:5]
	v_mfma_f32_16x16x32_bf16 v[54:57], v[166:169], v[182:185], v[54:57]
	v_mfma_f32_16x16x32_bf16 v[50:53], v[174:177], v[182:185], v[50:53]
	v_mfma_f32_16x16x32_bf16 v[38:41], v[166:169], v[198:201], v[38:41]
	v_mfma_f32_16x16x32_bf16 v[34:37], v[174:177], v[198:201], v[34:37]
	v_mfma_f32_16x16x32_bf16 v[22:25], v[166:169], v[206:209], v[22:25]
	v_mfma_f32_16x16x32_bf16 v[18:21], v[174:177], v[206:209], v[18:21]
	v_mfma_f32_16x16x32_bf16 v[6:9], v[166:169], v[216:219], v[6:9]
	v_mfma_f32_16x16x32_bf16 v[2:5], v[174:177], v[216:219], v[2:5]
	s_barrier
	s_add_i32 s59, s59, 2
	s_add_u32 s57, s57, 0x100
	s_addc_u32 s58, s58, 0
	s_cmpk_gt_u32 s59, 0xa9
	s_mov_b64 s[22:23], s[24:25]
	s_cbranch_scc0 .LBB0_1354
	s_setprio 0
	s_and_b64 vcc, exec, s[46:47]
	s_cbranch_vccz .LBB0_1357
	s_barrier

.LBB0_1404:
	s_add_u32 s51, s22, 0x100
	v_mov_b32_e32 v2, 0
	s_addc_u32 s52, s23, 0
	s_mov_b32 s53, -2
	v_mov_b32_e32 v3, v2
	v_mov_b32_e32 v4, v2
	s_waitcnt lgkmcnt(0)
	v_mov_b32_e32 v5, v2
	v_mov_b32_e32 v6, v2
	v_mov_b32_e32 v7, v2
	v_mov_b32_e32 v8, v2
	v_mov_b32_e32 v9, v2
	v_mov_b32_e32 v18, v2
	v_mov_b32_e32 v19, v2
	v_mov_b32_e32 v20, v2
	v_mov_b32_e32 v21, v2
	v_mov_b32_e32 v22, v2
	v_mov_b32_e32 v23, v2
	v_mov_b32_e32 v24, v2
	v_mov_b32_e32 v25, v2
	s_waitcnt vmcnt(0)
	v_mov_b32_e32 v34, v2
	v_mov_b32_e32 v35, v2
	v_mov_b32_e32 v36, v2
	v_mov_b32_e32 v37, v2
	v_mov_b32_e32 v38, v2
	v_mov_b32_e32 v39, v2
	v_mov_b32_e32 v40, v2
	v_mov_b32_e32 v41, v2
	v_mov_b32_e32 v50, v2
	v_mov_b32_e32 v51, v2
	v_mov_b32_e32 v52, v2
	v_mov_b32_e32 v53, v2
	v_mov_b32_e32 v54, v2
	v_mov_b32_e32 v55, v2
	v_mov_b32_e32 v56, v2
	v_mov_b32_e32 v57, v2
	v_mov_b32_e32 v10, v2
	v_mov_b32_e32 v11, v2
	v_mov_b32_e32 v12, v2
	v_mov_b32_e32 v13, v2
	v_mov_b32_e32 v14, v2
	v_mov_b32_e32 v15, v2
	v_mov_b32_e32 v16, v2
	v_mov_b32_e32 v17, v2
	v_mov_b32_e32 v26, v2
	v_mov_b32_e32 v27, v2
	v_mov_b32_e32 v28, v2
	v_mov_b32_e32 v29, v2
	v_mov_b32_e32 v30, v2
	v_mov_b32_e32 v31, v2
	v_mov_b32_e32 v32, v2
	v_mov_b32_e32 v33, v2
	v_mov_b32_e32 v42, v2
	v_mov_b32_e32 v43, v2
	v_mov_b32_e32 v44, v2
	v_mov_b32_e32 v45, v2
	v_mov_b32_e32 v46, v2
	v_mov_b32_e32 v47, v2
	v_mov_b32_e32 v48, v2
	v_mov_b32_e32 v49, v2
	v_mov_b32_e32 v58, v2
	v_mov_b32_e32 v59, v2
	v_mov_b32_e32 v60, v2
	v_mov_b32_e32 v61, v2
	v_mov_b32_e32 v62, v2
	v_mov_b32_e32 v63, v2
	v_mov_b32_e32 v64, v2
	v_mov_b32_e32 v65, v2
	v_mov_b32_e32 v66, v2
	v_mov_b32_e32 v67, v2
	v_mov_b32_e32 v68, v2
	v_mov_b32_e32 v69, v2
	v_mov_b32_e32 v70, v2
	v_mov_b32_e32 v71, v2
	v_mov_b32_e32 v72, v2
	v_mov_b32_e32 v73, v2
	v_mov_b32_e32 v82, v2
	v_mov_b32_e32 v83, v2
	v_mov_b32_e32 v84, v2
	v_mov_b32_e32 v85, v2
	v_mov_b32_e32 v86, v2
	v_mov_b32_e32 v87, v2
	v_mov_b32_e32 v88, v2
	v_mov_b32_e32 v89, v2
	v_mov_b32_e32 v98, v2
	v_mov_b32_e32 v99, v2
	v_mov_b32_e32 v100, v2
	v_mov_b32_e32 v101, v2
	v_mov_b32_e32 v102, v2
	v_mov_b32_e32 v103, v2
	v_mov_b32_e32 v104, v2
	v_mov_b32_e32 v105, v2
	v_mov_b32_e32 v114, v2
	v_mov_b32_e32 v115, v2
	v_mov_b32_e32 v116, v2
	v_mov_b32_e32 v117, v2
	v_mov_b32_e32 v118, v2
	v_mov_b32_e32 v119, v2
	v_mov_b32_e32 v120, v2
	v_mov_b32_e32 v121, v2
	v_mov_b32_e32 v74, v2
	v_mov_b32_e32 v75, v2
	v_mov_b32_e32 v76, v2
	v_mov_b32_e32 v77, v2
	v_mov_b32_e32 v78, v2
	v_mov_b32_e32 v79, v2
	v_mov_b32_e32 v80, v2
	v_mov_b32_e32 v81, v2
	v_mov_b32_e32 v90, v2
	v_mov_b32_e32 v91, v2
	v_mov_b32_e32 v92, v2
	v_mov_b32_e32 v93, v2
	v_mov_b32_e32 v94, v2
	v_mov_b32_e32 v95, v2
	v_mov_b32_e32 v96, v2
	v_mov_b32_e32 v97, v2
	v_mov_b32_e32 v106, v2
	v_mov_b32_e32 v107, v2
	v_mov_b32_e32 v108, v2
	v_mov_b32_e32 v109, v2
	v_mov_b32_e32 v110, v2
	v_mov_b32_e32 v111, v2
	v_mov_b32_e32 v112, v2
	v_mov_b32_e32 v113, v2
	v_mov_b32_e32 v122, v2
	v_mov_b32_e32 v123, v2
	v_mov_b32_e32 v124, v2
	v_mov_b32_e32 v125, v2
	v_mov_b32_e32 v126, v2
	v_mov_b32_e32 v127, v2
	v_mov_b32_e32 v128, v2
	v_mov_b32_e32 v129, v2
	v_readfirstlane_b32 s100, v0
	s_cmp_lt_u32 s100, 0x100
	s_cbranch_scc1 .Lprio_skip_1405
	s_setprio 1
.Lprio_skip_1405:
.LBB0_1405:
	s_add_u32 s22, s16, 0x100
	s_addc_u32 s23, s17, 0
	s_add_i32 s54, 0, 0x10000
	s_cmpk_eq_i32 s53, 0xa8
	s_cselect_b32 s27, s3, s23
	s_cselect_b32 s26, s2, s22
	v_add_u32_e32 v148, s54, v152
	s_cselect_b32 s25, s13, s52
	s_cselect_b32 s24, s12, s51
	s_add_i32 s55, 0, 0x14000
	ds_read_b128 v[144:147], v148
	ds_read_b128 v[156:159], v148 offset:1024
	ds_read_b128 v[160:163], v148 offset:2048
	ds_read_b128 v[164:167], v148 offset:3072
	v_add_u32_e32 v148, s55, v152
	ds_read_b128 v[168:171], v148
	ds_read_b128 v[172:175], v148 offset:1024
	ds_read_b128 v[176:179], v148 offset:2048
	ds_read_b128 v[180:183], v148 offset:3072
	v_lshl_add_u64 v[148:149], s[16:17], 0, v[140:141]
	s_add_i32 m0, s29, 0xc000
	ds_read_b128 v[184:187], v154
	ds_read_b128 v[188:191], v154 offset:1024
	ds_read_b128 v[192:195], v154 offset:2048
	ds_read_b128 v[196:199], v154 offset:3072
	ds_read_b128 v[200:203], v154 offset:4096
	ds_read_b128 v[204:207], v154 offset:5120
	ds_read_b128 v[208:211], v154 offset:6144
	ds_read_b128 v[216:219], v154 offset:7168
	global_load_lds_dwordx4 v[148:149], off
	v_lshl_add_u64 v[148:149], s[16:17], 0, v[142:143]
	s_add_i32 m0, s29, 0xe000
	s_nop 0
	global_load_lds_dwordx4 v[148:149], off
	s_waitcnt vmcnt(8)
	s_waitcnt lgkmcnt(0)
	s_barrier
	s_waitcnt lgkmcnt(0)
	v_mfma_f32_16x16x32_bf16 v[126:129], v[144:147], v[184:187], v[126:129]
	v_mfma_f32_16x16x32_bf16 v[122:125], v[160:163], v[184:187], v[122:125]
	v_mfma_f32_16x16x32_bf16 v[110:113], v[144:147], v[192:195], v[110:113]
	v_mfma_f32_16x16x32_bf16 v[106:109], v[160:163], v[192:195], v[106:109]
	v_mfma_f32_16x16x32_bf16 v[94:97], v[144:147], v[200:203], v[94:97]
	v_mfma_f32_16x16x32_bf16 v[90:93], v[160:163], v[200:203], v[90:93]
	v_mfma_f32_16x16x32_bf16 v[78:81], v[144:147], v[208:211], v[78:81]
	v_mfma_f32_16x16x32_bf16 v[74:77], v[160:163], v[208:211], v[74:77]
	v_mfma_f32_16x16x32_bf16 v[126:129], v[156:159], v[188:191], v[126:129]
	v_mfma_f32_16x16x32_bf16 v[122:125], v[164:167], v[188:191], v[122:125]
	v_mfma_f32_16x16x32_bf16 v[110:113], v[156:159], v[196:199], v[110:113]
	v_mfma_f32_16x16x32_bf16 v[106:109], v[164:167], v[196:199], v[106:109]
	v_mfma_f32_16x16x32_bf16 v[94:97], v[156:159], v[204:207], v[94:97]
	v_mfma_f32_16x16x32_bf16 v[90:93], v[164:167], v[204:207], v[90:93]
	v_mfma_f32_16x16x32_bf16 v[78:81], v[156:159], v[216:219], v[78:81]
	v_mfma_f32_16x16x32_bf16 v[74:77], v[164:167], v[216:219], v[74:77]
	v_mfma_f32_16x16x32_bf16 v[118:121], v[168:171], v[184:187], v[118:121]
	v_mfma_f32_16x16x32_bf16 v[114:117], v[176:179], v[184:187], v[114:117]
	v_mfma_f32_16x16x32_bf16 v[102:105], v[168:171], v[192:195], v[102:105]
	v_mfma_f32_16x16x32_bf16 v[98:101], v[176:179], v[192:195], v[98:101]
	v_mfma_f32_16x16x32_bf16 v[86:89], v[168:171], v[200:203], v[86:89]
	v_mfma_f32_16x16x32_bf16 v[82:85], v[176:179], v[200:203], v[82:85]
	v_mfma_f32_16x16x32_bf16 v[70:73], v[168:171], v[208:211], v[70:73]
	v_mfma_f32_16x16x32_bf16 v[66:69], v[176:179], v[208:211], v[66:69]
	v_mfma_f32_16x16x32_bf16 v[118:121], v[172:175], v[188:191], v[118:121]
	v_mfma_f32_16x16x32_bf16 v[114:117], v[180:183], v[188:191], v[114:117]
	v_mfma_f32_16x16x32_bf16 v[102:105], v[172:175], v[196:199], v[102:105]
	v_mfma_f32_16x16x32_bf16 v[98:101], v[180:183], v[196:199], v[98:101]
	v_mfma_f32_16x16x32_bf16 v[86:89], v[172:175], v[204:207], v[86:89]
	v_mfma_f32_16x16x32_bf16 v[82:85], v[180:183], v[204:207], v[82:85]
	v_mfma_f32_16x16x32_bf16 v[70:73], v[172:175], v[216:219], v[70:73]
	v_mfma_f32_16x16x32_bf16 v[66:69], v[180:183], v[216:219], v[66:69]
	s_barrier
	s_add_i32 s16, s54, s28
	v_lshl_add_u64 v[148:149], s[24:25], 0, v[130:131]
	s_mov_b32 m0, s16
	ds_read_b128 v[184:187], v154 offset:16384
	ds_read_b128 v[188:191], v154 offset:17408
	ds_read_b128 v[192:195], v154 offset:18432
	ds_read_b128 v[196:199], v154 offset:19456
	ds_read_b128 v[200:203], v154 offset:20480
	ds_read_b128 v[204:207], v154 offset:21504
	ds_read_b128 v[208:211], v154 offset:22528
	ds_read_b128 v[216:219], v154 offset:23552
	global_load_lds_dwordx4 v[148:149], off
	s_add_i32 m0, s16, 0x2000
	s_add_u32 s16, s24, 0x2b0000
	v_lshl_add_u64 v[212:213], s[24:25], 0, v[132:133]
	s_addc_u32 s17, s25, 0
	s_add_i32 s54, s55, s28
	global_load_lds_dwordx4 v[212:213], off
	v_lshl_add_u64 v[220:221], s[16:17], 0, v[130:131]
	s_mov_b32 m0, s54
	v_lshl_add_u64 v[222:223], s[26:27], 0, v[134:135]
	global_load_lds_dwordx4 v[220:221], off
	v_lshl_add_u64 v[220:221], s[16:17], 0, v[132:133]
	s_add_i32 m0, s54, 0x2000
	s_nop 0
	global_load_lds_dwordx4 v[220:221], off
	v_lshl_add_u64 v[220:221], s[26:27], 0, v[136:137]
	s_mov_b32 m0, s29
	s_nop 0
	global_load_lds_dwordx4 v[220:221], off
	s_mov_b32 m0, s30
	s_nop 0
	global_load_lds_dwordx4 v[222:223], off
	s_waitcnt vmcnt(8)
	s_waitcnt lgkmcnt(0)
	s_barrier
	s_waitcnt lgkmcnt(0)
	v_mfma_f32_16x16x32_bf16 v[62:65], v[144:147], v[184:187], v[62:65]
	v_mfma_f32_16x16x32_bf16 v[58:61], v[160:163], v[184:187], v[58:61]
	v_mfma_f32_16x16x32_bf16 v[46:49], v[144:147], v[192:195], v[46:49]
	v_mfma_f32_16x16x32_bf16 v[42:45], v[160:163], v[192:195], v[42:45]
	v_mfma_f32_16x16x32_bf16 v[30:33], v[144:147], v[200:203], v[30:33]
	v_mfma_f32_16x16x32_bf16 v[26:29], v[160:163], v[200:203], v[26:29]
	v_mfma_f32_16x16x32_bf16 v[14:17], v[144:147], v[208:211], v[14:17]
	v_mfma_f32_16x16x32_bf16 v[10:13], v[160:163], v[208:211], v[10:13]
	v_mfma_f32_16x16x32_bf16 v[62:65], v[156:159], v[188:191], v[62:65]
	v_mfma_f32_16x16x32_bf16 v[58:61], v[164:167], v[188:191], v[58:61]
	v_mfma_f32_16x16x32_bf16 v[46:49], v[156:159], v[196:199], v[46:49]
	v_mfma_f32_16x16x32_bf16 v[42:45], v[164:167], v[196:199], v[42:45]
	v_mfma_f32_16x16x32_bf16 v[30:33], v[156:159], v[204:207], v[30:33]
	v_mfma_f32_16x16x32_bf16 v[26:29], v[164:167], v[204:207], v[26:29]
	v_mfma_f32_16x16x32_bf16 v[14:17], v[156:159], v[216:219], v[14:17]
	v_mfma_f32_16x16x32_bf16 v[10:13], v[164:167], v[216:219], v[10:13]
	v_mfma_f32_16x16x32_bf16 v[54:57], v[168:171], v[184:187], v[54:57]
	v_mfma_f32_16x16x32_bf16 v[50:53], v[176:179], v[184:187], v[50:53]
	v_mfma_f32_16x16x32_bf16 v[38:41], v[168:171], v[192:195], v[38:41]
	v_mfma_f32_16x16x32_bf16 v[34:37], v[176:179], v[192:195], v[34:37]
	v_mfma_f32_16x16x32_bf16 v[22:25], v[168:171], v[200:203], v[22:25]
	v_mfma_f32_16x16x32_bf16 v[18:21], v[176:179], v[200:203], v[18:21]
	v_mfma_f32_16x16x32_bf16 v[6:9], v[168:171], v[208:211], v[6:9]
	v_mfma_f32_16x16x32_bf16 v[2:5], v[176:179], v[208:211], v[2:5]
	v_mfma_f32_16x16x32_bf16 v[54:57], v[172:175], v[188:191], v[54:57]
	v_mfma_f32_16x16x32_bf16 v[50:53], v[180:183], v[188:191], v[50:53]
	v_mfma_f32_16x16x32_bf16 v[38:41], v[172:175], v[196:199], v[38:41]
	v_mfma_f32_16x16x32_bf16 v[34:37], v[180:183], v[196:199], v[34:37]
	v_mfma_f32_16x16x32_bf16 v[22:25], v[172:175], v[204:207], v[22:25]
	v_mfma_f32_16x16x32_bf16 v[18:21], v[180:183], v[204:207], v[18:21]
	v_mfma_f32_16x16x32_bf16 v[6:9], v[172:175], v[216:219], v[6:9]
	v_mfma_f32_16x16x32_bf16 v[2:5], v[180:183], v[216:219], v[2:5]
	s_barrier
	s_add_i32 s54, 0, 0x18000
	v_add_u32_e32 v155, s54, v152
	s_add_i32 s55, 0, 0x1c000
	ds_read_b128 v[144:147], v155
	ds_read_b128 v[156:159], v155 offset:1024
	ds_read_b128 v[160:163], v155 offset:2048
	ds_read_b128 v[164:167], v155 offset:3072
	v_add_u32_e32 v155, s55, v152
	ds_read_b128 v[168:171], v155
	ds_read_b128 v[172:175], v155 offset:1024
	ds_read_b128 v[176:179], v155 offset:2048
	ds_read_b128 v[180:183], v155 offset:3072
	s_add_u32 s16, s26, 0x2b0000
	s_addc_u32 s17, s27, 0
	s_mov_b32 m0, s40
	v_lshl_add_u64 v[224:225], s[16:17], 0, v[136:137]
	ds_read_b128 v[184:187], v154 offset:32768
	ds_read_b128 v[188:191], v154 offset:33792
	ds_read_b128 v[192:195], v154 offset:34816
	ds_read_b128 v[196:199], v154 offset:35840
	ds_read_b128 v[200:203], v154 offset:36864
	ds_read_b128 v[204:207], v154 offset:37888
	ds_read_b128 v[208:211], v154 offset:38912
	ds_read_b128 v[216:219], v154 offset:39936
	global_load_lds_dwordx4 v[224:225], off
	v_lshl_add_u64 v[224:225], s[16:17], 0, v[134:135]
	s_mov_b32 m0, s41
	s_nop 0
	global_load_lds_dwordx4 v[224:225], off
	s_waitcnt vmcnt(8)
	s_waitcnt lgkmcnt(0)
	s_barrier
	s_waitcnt lgkmcnt(0)
	v_mfma_f32_16x16x32_bf16 v[126:129], v[144:147], v[184:187], v[126:129]
	v_mfma_f32_16x16x32_bf16 v[122:125], v[160:163], v[184:187], v[122:125]
	v_mfma_f32_16x16x32_bf16 v[110:113], v[144:147], v[192:195], v[110:113]
	v_mfma_f32_16x16x32_bf16 v[106:109], v[160:163], v[192:195], v[106:109]
	v_mfma_f32_16x16x32_bf16 v[94:97], v[144:147], v[200:203], v[94:97]
	v_mfma_f32_16x16x32_bf16 v[90:93], v[160:163], v[200:203], v[90:93]
	v_mfma_f32_16x16x32_bf16 v[78:81], v[144:147], v[208:211], v[78:81]
	v_mfma_f32_16x16x32_bf16 v[74:77], v[160:163], v[208:211], v[74:77]
	v_mfma_f32_16x16x32_bf16 v[126:129], v[156:159], v[188:191], v[126:129]
	v_mfma_f32_16x16x32_bf16 v[122:125], v[164:167], v[188:191], v[122:125]
	v_mfma_f32_16x16x32_bf16 v[110:113], v[156:159], v[196:199], v[110:113]
	v_mfma_f32_16x16x32_bf16 v[106:109], v[164:167], v[196:199], v[106:109]
	v_mfma_f32_16x16x32_bf16 v[94:97], v[156:159], v[204:207], v[94:97]
	v_mfma_f32_16x16x32_bf16 v[90:93], v[164:167], v[204:207], v[90:93]
	v_mfma_f32_16x16x32_bf16 v[78:81], v[156:159], v[216:219], v[78:81]
	v_mfma_f32_16x16x32_bf16 v[74:77], v[164:167], v[216:219], v[74:77]
	v_mfma_f32_16x16x32_bf16 v[118:121], v[168:171], v[184:187], v[118:121]
	v_mfma_f32_16x16x32_bf16 v[114:117], v[176:179], v[184:187], v[114:117]
	v_mfma_f32_16x16x32_bf16 v[102:105], v[168:171], v[192:195], v[102:105]
	v_mfma_f32_16x16x32_bf16 v[98:101], v[176:179], v[192:195], v[98:101]
	v_mfma_f32_16x16x32_bf16 v[86:89], v[168:171], v[200:203], v[86:89]
	v_mfma_f32_16x16x32_bf16 v[82:85], v[176:179], v[200:203], v[82:85]
	v_mfma_f32_16x16x32_bf16 v[70:73], v[168:171], v[208:211], v[70:73]
	v_mfma_f32_16x16x32_bf16 v[66:69], v[176:179], v[208:211], v[66:69]
	v_mfma_f32_16x16x32_bf16 v[118:121], v[172:175], v[188:191], v[118:121]
	v_mfma_f32_16x16x32_bf16 v[114:117], v[180:183], v[188:191], v[114:117]
	v_mfma_f32_16x16x32_bf16 v[102:105], v[172:175], v[196:199], v[102:105]
	v_mfma_f32_16x16x32_bf16 v[98:101], v[180:183], v[196:199], v[98:101]
	v_mfma_f32_16x16x32_bf16 v[86:89], v[172:175], v[204:207], v[86:89]
	v_mfma_f32_16x16x32_bf16 v[82:85], v[180:183], v[204:207], v[82:85]
	v_mfma_f32_16x16x32_bf16 v[70:73], v[172:175], v[216:219], v[70:73]
	v_mfma_f32_16x16x32_bf16 v[66:69], v[180:183], v[216:219], v[66:69]
	s_barrier
	s_add_i32 s16, s54, s28
	v_lshl_add_u64 v[148:149], v[148:149], 0, s[18:19]
	s_mov_b32 m0, s16
	ds_read_b128 v[184:187], v154 offset:49152
	ds_read_b128 v[188:191], v154 offset:50176
	ds_read_b128 v[192:195], v154 offset:51200
	ds_read_b128 v[196:199], v154 offset:52224
	ds_read_b128 v[200:203], v154 offset:53248
	ds_read_b128 v[204:207], v154 offset:54272
	ds_read_b128 v[208:211], v154 offset:55296
	ds_read_b128 v[216:219], v154 offset:56320
	global_load_lds_dwordx4 v[148:149], off
	s_add_i32 m0, s16, 0x2000
	s_add_u32 s16, s24, 0x2b0080
	v_lshl_add_u64 v[148:149], v[212:213], 0, s[18:19]
	s_addc_u32 s17, s25, 0
	s_add_i32 s24, s55, s28
	global_load_lds_dwordx4 v[148:149], off
	v_lshl_add_u64 v[148:149], s[16:17], 0, v[130:131]
	s_mov_b32 m0, s24
	s_nop 0
	global_load_lds_dwordx4 v[148:149], off
	v_lshl_add_u64 v[148:149], s[16:17], 0, v[132:133]
	s_add_i32 m0, s24, 0x2000
	s_nop 0
	global_load_lds_dwordx4 v[148:149], off
	v_lshl_add_u64 v[148:149], v[220:221], 0, s[18:19]
	s_mov_b32 m0, s44
	s_nop 0
	global_load_lds_dwordx4 v[148:149], off
	v_lshl_add_u64 v[148:149], v[222:223], 0, s[18:19]
	s_mov_b32 m0, s45
	s_nop 0
	global_load_lds_dwordx4 v[148:149], off
	s_waitcnt vmcnt(8)
	s_waitcnt lgkmcnt(0)
	s_barrier
	s_waitcnt lgkmcnt(0)
	v_mfma_f32_16x16x32_bf16 v[62:65], v[144:147], v[184:187], v[62:65]
	v_mfma_f32_16x16x32_bf16 v[58:61], v[160:163], v[184:187], v[58:61]
	v_mfma_f32_16x16x32_bf16 v[46:49], v[144:147], v[192:195], v[46:49]
	v_mfma_f32_16x16x32_bf16 v[42:45], v[160:163], v[192:195], v[42:45]
	v_mfma_f32_16x16x32_bf16 v[30:33], v[144:147], v[200:203], v[30:33]
	v_mfma_f32_16x16x32_bf16 v[26:29], v[160:163], v[200:203], v[26:29]
	v_mfma_f32_16x16x32_bf16 v[14:17], v[144:147], v[208:211], v[14:17]
	v_mfma_f32_16x16x32_bf16 v[10:13], v[160:163], v[208:211], v[10:13]
	v_mfma_f32_16x16x32_bf16 v[62:65], v[156:159], v[188:191], v[62:65]
	v_mfma_f32_16x16x32_bf16 v[58:61], v[164:167], v[188:191], v[58:61]
	v_mfma_f32_16x16x32_bf16 v[46:49], v[156:159], v[196:199], v[46:49]
	v_mfma_f32_16x16x32_bf16 v[42:45], v[164:167], v[196:199], v[42:45]
	v_mfma_f32_16x16x32_bf16 v[30:33], v[156:159], v[204:207], v[30:33]
	v_mfma_f32_16x16x32_bf16 v[26:29], v[164:167], v[204:207], v[26:29]
	v_mfma_f32_16x16x32_bf16 v[14:17], v[156:159], v[216:219], v[14:17]
	v_mfma_f32_16x16x32_bf16 v[10:13], v[164:167], v[216:219], v[10:13]
	v_mfma_f32_16x16x32_bf16 v[54:57], v[168:171], v[184:187], v[54:57]
	v_mfma_f32_16x16x32_bf16 v[50:53], v[176:179], v[184:187], v[50:53]
	v_mfma_f32_16x16x32_bf16 v[38:41], v[168:171], v[192:195], v[38:41]
	v_mfma_f32_16x16x32_bf16 v[34:37], v[176:179], v[192:195], v[34:37]
	v_mfma_f32_16x16x32_bf16 v[22:25], v[168:171], v[200:203], v[22:25]
	v_mfma_f32_16x16x32_bf16 v[18:21], v[176:179], v[200:203], v[18:21]
	v_mfma_f32_16x16x32_bf16 v[6:9], v[168:171], v[208:211], v[6:9]
	v_mfma_f32_16x16x32_bf16 v[2:5], v[176:179], v[208:211], v[2:5]
	v_mfma_f32_16x16x32_bf16 v[54:57], v[172:175], v[188:191], v[54:57]
	v_mfma_f32_16x16x32_bf16 v[50:53], v[180:183], v[188:191], v[50:53]
	v_mfma_f32_16x16x32_bf16 v[38:41], v[172:175], v[196:199], v[38:41]
	v_mfma_f32_16x16x32_bf16 v[34:37], v[180:183], v[196:199], v[34:37]
	v_mfma_f32_16x16x32_bf16 v[22:25], v[172:175], v[204:207], v[22:25]
	v_mfma_f32_16x16x32_bf16 v[18:21], v[180:183], v[204:207], v[18:21]
	v_mfma_f32_16x16x32_bf16 v[6:9], v[172:175], v[216:219], v[6:9]
	v_mfma_f32_16x16x32_bf16 v[2:5], v[180:183], v[216:219], v[2:5]
	s_barrier
	s_add_i32 s53, s53, 2
	s_add_u32 s51, s51, 0x100
	s_addc_u32 s52, s52, 0
	s_cmpk_gt_u32 s53, 0xa9
	s_mov_b64 s[16:17], s[22:23]
	s_cbranch_scc0 .LBB0_1405
	s_setprio 0
	s_and_b64 vcc, exec, s[6:7]
	s_cbranch_vccz .LBB0_1408
	s_barrier
